# S5 scan: B*u product taken with state on the lane (swapped MFMA operands + half-wave exchange), recurrence from registers in both passes
# speedup vs baseline: 1.2223x; 1.0094x over previous
; DI bf16_t f2bf(float x) { unsigned u = __float_as_uint(x); u += 0x7fffu + ((u >> 16) & 1u); return (bf16_t)(u >> 16); }
; template <bool PASS2>
; DI void s5_item(const Params& p, int l, int item, int lane, const bf16_t* ubuf, bf16_t* ybpre, bf16_t* xs, float* bus) {
;     ...
;   for (int tb = 0; tb < LC5; tb += 32) {
;     const bf16x8 uf = *(const bf16x8*)(ubuf + (tok0 + tb + r) * 512 + g * 16 + 8 * hh);
;     f32x16 D[4];
; #pragma unroll
;     for (int mt = 0; mt < 4; mt++) {
; #pragma unroll
;       for (int i = 0; i < 16; i++) D[mt][i] = 0.f;
;       D[mt] = __builtin_amdgcn_mfma_f32_32x32x16_bf16(bf_[mt], uf, D[mt], 0, 0, 0);
;     }
; #pragma unroll
;     for (int half = 0; half < 2; half++) {
;       __builtin_amdgcn_fence(__ATOMIC_RELEASE, "wavefront");
;       __builtin_amdgcn_wave_barrier();
;       if ((r >> 4) == half) {
; #pragma unroll
;         for (int mt = 0; mt < 4; mt++)
; #pragma unroll
;           for (int i = 0; i < 16; i++)
;             bus[(32 * mt + (i & 3) + 8 * (i >> 2) + 4 * hh) * 17 + (r & 15)] = D[mt][i];
;       }
;       __builtin_amdgcn_fence(__ATOMIC_RELEASE, "wavefront");
;       __builtin_amdgcn_wave_barrier();
;       __builtin_amdgcn_fence(__ATOMIC_ACQUIRE, "wavefront");
; #pragma unroll 4
;       for (int t = 0; t < 16; t++) {
;         const float bur = bus[lane * 17 + t], bui = bus[(64 + lane) * 17 + t];
;         const float nxr = ar * xr - ai * xi + bur, nxi = ar * xi + ai * xr + bui;
;         xr = nxr; xi = nxi;
;         if (PASS2) {
;           xs[(half * 16 + t) * XSP + lane] = f2bf(xr);
;           xs[(half * 16 + t) * XSP + 64 + lane] = f2bf(xi);
;         }
;       }
;     }
.LBB0_526:
	v_lshl_add_u64 v[0:1], v[92:93], 0, s[6:7]
	v_lshlrev_b64 v[0:1], 10, v[0:1]
	v_lshl_add_u64 v[0:1], v[90:91], 0, v[0:1]
	global_load_dwordx4 v[0:3], v[0:1], off
	s_waitcnt vmcnt(0)
	v_mov_b32_e32 v114, v0
	v_mov_b32_e32 v115, v1
	v_mov_b32_e32 v116, v2
	v_mov_b32_e32 v117, v3
	s_nop 1
	v_mfma_f32_32x32x16_bf16 v[48:63], v[114:117], v[64:67], 0
	v_mfma_f32_32x32x16_bf16 v[32:47], v[114:117], v[68:71], 0
	v_mfma_f32_32x32x16_bf16 v[16:31], v[114:117], v[72:75], 0
	v_mfma_f32_32x32x16_bf16 v[0:15], v[114:117], v[76:79], 0
	s_nop 7
	s_nop 3
	v_permlane32_swap_b32 v48, v32
	v_permlane32_swap_b32 v49, v33
	v_permlane32_swap_b32 v50, v34
	v_permlane32_swap_b32 v51, v35
	v_permlane32_swap_b32 v52, v36
	v_permlane32_swap_b32 v53, v37
	v_permlane32_swap_b32 v54, v38
	v_permlane32_swap_b32 v55, v39
	v_permlane32_swap_b32 v56, v40
	v_permlane32_swap_b32 v57, v41
	v_permlane32_swap_b32 v58, v42
	v_permlane32_swap_b32 v59, v43
	v_permlane32_swap_b32 v60, v44
	v_permlane32_swap_b32 v61, v45
	v_permlane32_swap_b32 v62, v46
	v_permlane32_swap_b32 v63, v47
	v_permlane32_swap_b32 v16, v0
	v_permlane32_swap_b32 v17, v1
	v_permlane32_swap_b32 v18, v2
	v_permlane32_swap_b32 v19, v3
	v_permlane32_swap_b32 v20, v4
	v_permlane32_swap_b32 v21, v5
	v_permlane32_swap_b32 v22, v6
	v_permlane32_swap_b32 v23, v7
	v_permlane32_swap_b32 v24, v8
	v_permlane32_swap_b32 v25, v9
	v_permlane32_swap_b32 v26, v10
	v_permlane32_swap_b32 v27, v11
	v_permlane32_swap_b32 v28, v12
	v_permlane32_swap_b32 v29, v13
	v_permlane32_swap_b32 v30, v14
	v_permlane32_swap_b32 v31, v15
	v_fma_f32 v112, v88, v96, v48
	v_fma_f32 v113, v88, v98, v16
	v_fma_f32 v112, -v89, v98, v112
	v_fma_f32 v113, v89, v96, v113
	v_fma_f32 v96, v88, v112, v49
	v_fma_f32 v98, v88, v113, v17
	v_fma_f32 v96, -v89, v113, v96
	v_fma_f32 v98, v89, v112, v98
	v_fma_f32 v112, v88, v96, v50
	v_fma_f32 v113, v88, v98, v18
	v_fma_f32 v112, -v89, v98, v112
	v_fma_f32 v113, v89, v96, v113
	v_fma_f32 v96, v88, v112, v51
	v_fma_f32 v98, v88, v113, v19
	v_fma_f32 v96, -v89, v113, v96
	v_fma_f32 v98, v89, v112, v98
	v_fma_f32 v112, v88, v96, v32
	v_fma_f32 v113, v88, v98, v0
	v_fma_f32 v112, -v89, v98, v112
	v_fma_f32 v113, v89, v96, v113
	v_fma_f32 v96, v88, v112, v33
	v_fma_f32 v98, v88, v113, v1
	v_fma_f32 v96, -v89, v113, v96
	v_fma_f32 v98, v89, v112, v98
	v_fma_f32 v112, v88, v96, v34
	v_fma_f32 v113, v88, v98, v2
	v_fma_f32 v112, -v89, v98, v112
	v_fma_f32 v113, v89, v96, v113
	v_fma_f32 v96, v88, v112, v35
	v_fma_f32 v98, v88, v113, v3
	v_fma_f32 v96, -v89, v113, v96
	v_fma_f32 v98, v89, v112, v98
	v_fma_f32 v112, v88, v96, v52
	v_fma_f32 v113, v88, v98, v20
	v_fma_f32 v112, -v89, v98, v112
	v_fma_f32 v113, v89, v96, v113
	v_fma_f32 v96, v88, v112, v53
	v_fma_f32 v98, v88, v113, v21
	v_fma_f32 v96, -v89, v113, v96
	v_fma_f32 v98, v89, v112, v98
	v_fma_f32 v112, v88, v96, v54
	v_fma_f32 v113, v88, v98, v22
	v_fma_f32 v112, -v89, v98, v112
	v_fma_f32 v113, v89, v96, v113
	v_fma_f32 v96, v88, v112, v55
	v_fma_f32 v98, v88, v113, v23
	v_fma_f32 v96, -v89, v113, v96
	v_fma_f32 v98, v89, v112, v98
	v_fma_f32 v112, v88, v96, v36
	v_fma_f32 v113, v88, v98, v4
	v_fma_f32 v112, -v89, v98, v112
	v_fma_f32 v113, v89, v96, v113
	v_fma_f32 v96, v88, v112, v37
	v_fma_f32 v98, v88, v113, v5
	v_fma_f32 v96, -v89, v113, v96
	v_fma_f32 v98, v89, v112, v98
	v_fma_f32 v112, v88, v96, v38
	v_fma_f32 v113, v88, v98, v6
	v_fma_f32 v112, -v89, v98, v112
	v_fma_f32 v113, v89, v96, v113
	v_fma_f32 v96, v88, v112, v39
	v_fma_f32 v98, v88, v113, v7
	v_fma_f32 v96, -v89, v113, v96
	v_fma_f32 v98, v89, v112, v98
	v_fma_f32 v112, v88, v96, v56
	v_fma_f32 v113, v88, v98, v24
	v_fma_f32 v112, -v89, v98, v112
	v_fma_f32 v113, v89, v96, v113
	v_fma_f32 v96, v88, v112, v57
	v_fma_f32 v98, v88, v113, v25
	v_fma_f32 v96, -v89, v113, v96
	v_fma_f32 v98, v89, v112, v98
	v_fma_f32 v112, v88, v96, v58
	v_fma_f32 v113, v88, v98, v26
	v_fma_f32 v112, -v89, v98, v112
	v_fma_f32 v113, v89, v96, v113
	v_fma_f32 v96, v88, v112, v59
	v_fma_f32 v98, v88, v113, v27
	v_fma_f32 v96, -v89, v113, v96
	v_fma_f32 v98, v89, v112, v98
	v_fma_f32 v112, v88, v96, v40
	v_fma_f32 v113, v88, v98, v8
	v_fma_f32 v112, -v89, v98, v112
	v_fma_f32 v113, v89, v96, v113
	v_fma_f32 v96, v88, v112, v41
	v_fma_f32 v98, v88, v113, v9
	v_fma_f32 v96, -v89, v113, v96
	v_fma_f32 v98, v89, v112, v98
	v_fma_f32 v112, v88, v96, v42
	v_fma_f32 v113, v88, v98, v10
	v_fma_f32 v112, -v89, v98, v112
	v_fma_f32 v113, v89, v96, v113
	v_fma_f32 v96, v88, v112, v43
	v_fma_f32 v98, v88, v113, v11
	v_fma_f32 v96, -v89, v113, v96
	v_fma_f32 v98, v89, v112, v98
	v_fma_f32 v112, v88, v96, v60
	v_fma_f32 v113, v88, v98, v28
	v_fma_f32 v112, -v89, v98, v112
	v_fma_f32 v113, v89, v96, v113
	v_fma_f32 v96, v88, v112, v61
	v_fma_f32 v98, v88, v113, v29
	v_fma_f32 v96, -v89, v113, v96
	v_fma_f32 v98, v89, v112, v98
	v_fma_f32 v112, v88, v96, v62
	v_fma_f32 v113, v88, v98, v30
	v_fma_f32 v112, -v89, v98, v112
	v_fma_f32 v113, v89, v96, v113
	v_fma_f32 v96, v88, v112, v63
	v_fma_f32 v98, v88, v113, v31
	v_fma_f32 v96, -v89, v113, v96
	v_fma_f32 v98, v89, v112, v98
	v_fma_f32 v112, v88, v96, v44
	v_fma_f32 v113, v88, v98, v12
	v_fma_f32 v112, -v89, v98, v112
	v_fma_f32 v113, v89, v96, v113
	v_fma_f32 v96, v88, v112, v45
	v_fma_f32 v98, v88, v113, v13
	v_fma_f32 v96, -v89, v113, v96
	v_fma_f32 v98, v89, v112, v98
	v_fma_f32 v112, v88, v96, v46
	v_fma_f32 v113, v88, v98, v14
	v_fma_f32 v112, -v89, v98, v112
	v_fma_f32 v113, v89, v96, v113
	v_fma_f32 v96, v88, v112, v47
	v_fma_f32 v98, v88, v113, v15
	v_fma_f32 v96, -v89, v113, v96
	v_fma_f32 v98, v89, v112, v98
	v_mov_b32_e32 v97, v98
	s_add_i32 s5, s6, 32
	s_cmpk_gt_u32 s6, 0x5f
	v_mov_b32_e32 v98, v97
	s_mov_b32 s6, s5
	s_cbranch_scc0 .LBB0_526
	s_lshl_b32 s4, s4, 12
	s_lshl_b32 s5, s16, 7
	s_add_i32 s4, s4, s12
	s_add_i32 s4, s4, s5
	s_ashr_i32 s5, s4, 31
	s_lshl_b64 s[4:5], s[4:5], 9
	v_lshl_add_u64 v[0:1], v[84:85], 0, s[4:5]
	v_readlane_b32 s4, v252, 27
	v_readlane_b32 s5, v252, 28
	global_store_dwordx2 v[0:1], v[96:97], off
	v_add_u32_e32 v99, s4, v99
	s_movk_i32 s4, 0x1fff
	v_cmp_lt_i32_e64 s[4:5], s4, v99
	s_or_b64 s[10:11], s[4:5], s[10:11]
	s_andn2_b64 exec, exec, s[10:11]
	s_cbranch_execnz .LBB0_525

; DI bf16_t f2bf(float x) { unsigned u = __float_as_uint(x); u += 0x7fffu + ((u >> 16) & 1u); return (bf16_t)(u >> 16); }
; template <bool PASS2>
; DI void s5_item(const Params& p, int l, int item, int lane, const bf16_t* ubuf, bf16_t* ybpre, bf16_t* xs, float* bus) {
;     ...
;   for (int tb = 0; tb < LC5; tb += 32) {
;     const bf16x8 uf = *(const bf16x8*)(ubuf + (tok0 + tb + r) * 512 + g * 16 + 8 * hh);
;     f32x16 D[4];
; #pragma unroll
;     for (int mt = 0; mt < 4; mt++) {
; #pragma unroll
;       for (int i = 0; i < 16; i++) D[mt][i] = 0.f;
;       D[mt] = __builtin_amdgcn_mfma_f32_32x32x16_bf16(bf_[mt], uf, D[mt], 0, 0, 0);
;     }
; #pragma unroll
;     for (int half = 0; half < 2; half++) {
;       __builtin_amdgcn_fence(__ATOMIC_RELEASE, "wavefront");
;       __builtin_amdgcn_wave_barrier();
;       if ((r >> 4) == half) {
; #pragma unroll
;         for (int mt = 0; mt < 4; mt++)
; #pragma unroll
;           for (int i = 0; i < 16; i++)
;             bus[(32 * mt + (i & 3) + 8 * (i >> 2) + 4 * hh) * 17 + (r & 15)] = D[mt][i];
;       }
;       __builtin_amdgcn_fence(__ATOMIC_RELEASE, "wavefront");
;       __builtin_amdgcn_wave_barrier();
;       __builtin_amdgcn_fence(__ATOMIC_ACQUIRE, "wavefront");
; #pragma unroll 4
;       for (int t = 0; t < 16; t++) {
;         const float bur = bus[lane * 17 + t], bui = bus[(64 + lane) * 17 + t];
;         const float nxr = ar * xr - ai * xi + bur, nxi = ar * xi + ai * xr + bui;
;         xr = nxr; xi = nxi;
;         if (PASS2) {
;           xs[(half * 16 + t) * XSP + lane] = f2bf(xr);
;           xs[(half * 16 + t) * XSP + 64 + lane] = f2bf(xi);
;         }
;       }
.LBB0_786:
	v_lshl_add_u64 v[140:141], v[130:131], 0, s[10:11]
	v_lshlrev_b64 v[0:1], 10, v[140:141]
	v_lshl_add_u64 v[138:139], s[4:5], 0, v[0:1]
	v_lshl_add_u64 v[0:1], v[138:139], 0, v[114:115]
	v_lshl_add_u64 v[208:209], v[0:1], 0, s[98:99]
	v_mov_b32_e32 v206, v124
	v_mov_b32_e32 v207, v115
	v_lshl_add_u64 v[206:207], v[138:139], 0, v[206:207]
	global_load_dwordx2 v[220:221], v[206:207], off
	global_load_dwordx2 v[222:223], v[206:207], off offset:16
	v_add_u32_e32 v190, 0x8800, v144
	v_add_u32_e32 v189, 0x8c00, v144
	v_add_u32_e32 v187, 0x9000, v144
	v_add_u32_e32 v188, 0x9400, v144
	v_add_u32_e32 v186, 0x9800, v144
	v_add_u32_e32 v184, 0x9c00, v144
	v_add_u32_e32 v185, 0x9e00, v144
	v_add_u32_e32 v183, 0xa000, v144
	v_add_u32_e32 v125, 0xa400, v144
	v_add_u32_e32 v181, 0xa600, v144
	v_add_u32_e32 v182, 0xa800, v144
	s_waitcnt vmcnt(4)
	v_mfma_f32_32x32x16_bf16 v[48:63], v[202:205], v[64:67], 0
	v_mfma_f32_32x32x16_bf16 v[32:47], v[202:205], v[68:71], 0
	v_mfma_f32_32x32x16_bf16 v[0:15], v[202:205], v[72:75], 0
	v_mfma_f32_32x32x16_bf16 v[16:31], v[202:205], v[76:79], 0
	global_load_dwordx4 v[202:205], v[208:209], off
	v_lshlrev_b64 v[140:141], 9, v[140:141]
	s_nop 7
	s_nop 1
	v_permlane32_swap_b32 v48, v32
	v_permlane32_swap_b32 v49, v33
	v_permlane32_swap_b32 v50, v34
	v_permlane32_swap_b32 v51, v35
	v_permlane32_swap_b32 v52, v36
	v_permlane32_swap_b32 v53, v37
	v_permlane32_swap_b32 v54, v38
	v_permlane32_swap_b32 v55, v39
	v_permlane32_swap_b32 v56, v40
	v_permlane32_swap_b32 v57, v41
	v_permlane32_swap_b32 v58, v42
	v_permlane32_swap_b32 v59, v43
	v_permlane32_swap_b32 v60, v44
	v_permlane32_swap_b32 v61, v45
	v_permlane32_swap_b32 v62, v46
	v_permlane32_swap_b32 v63, v47
	v_permlane32_swap_b32 v0, v16
	v_permlane32_swap_b32 v1, v17
	v_permlane32_swap_b32 v2, v18
	v_permlane32_swap_b32 v3, v19
	v_permlane32_swap_b32 v4, v20
	v_permlane32_swap_b32 v5, v21
	v_permlane32_swap_b32 v6, v22
	v_permlane32_swap_b32 v7, v23
	v_permlane32_swap_b32 v8, v24
	v_permlane32_swap_b32 v9, v25
	v_permlane32_swap_b32 v10, v26
	v_permlane32_swap_b32 v11, v27
	v_permlane32_swap_b32 v12, v28
	v_permlane32_swap_b32 v13, v29
	v_permlane32_swap_b32 v14, v30
	v_permlane32_swap_b32 v15, v31
	v_fma_f32 v194, v126, v128, v48
	v_fma_f32 v195, v126, v129, v0
	v_fma_f32 v194, -v127, v129, v194
	v_fma_f32 v195, v127, v128, v195
	v_bfe_u32 v196, v194, 16, 1
	v_bfe_u32 v197, v195, 16, 1
	v_add3_u32 v196, v194, v196, s22
	v_add3_u32 v197, v195, v197, s22
	ds_write_b16_d16_hi v145, v196 offset:0
	ds_write_b16_d16_hi v145, v197 offset:128
	v_fma_f32 v128, v126, v194, v49
	v_fma_f32 v129, v126, v195, v1
	v_fma_f32 v128, -v127, v195, v128
	v_fma_f32 v129, v127, v194, v129
	v_bfe_u32 v196, v128, 16, 1
	v_bfe_u32 v197, v129, 16, 1
	v_add3_u32 v196, v128, v196, s22
	v_add3_u32 v197, v129, v197, s22
	ds_write_b16_d16_hi v145, v196 offset:272
	ds_write_b16_d16_hi v145, v197 offset:400
	v_fma_f32 v194, v126, v128, v50
	v_fma_f32 v195, v126, v129, v2
	v_fma_f32 v194, -v127, v129, v194
	v_fma_f32 v195, v127, v128, v195
	v_bfe_u32 v196, v194, 16, 1
	v_bfe_u32 v197, v195, 16, 1
	v_add3_u32 v196, v194, v196, s22
	v_add3_u32 v197, v195, v197, s22
	ds_write_b16_d16_hi v145, v196 offset:544
	ds_write_b16_d16_hi v145, v197 offset:672
	v_fma_f32 v128, v126, v194, v51
	v_fma_f32 v129, v126, v195, v3
	v_fma_f32 v128, -v127, v195, v128
	v_fma_f32 v129, v127, v194, v129
	v_bfe_u32 v196, v128, 16, 1
	v_bfe_u32 v197, v129, 16, 1
	v_add3_u32 v196, v128, v196, s22
	v_add3_u32 v197, v129, v197, s22
	ds_write_b16_d16_hi v145, v196 offset:816
	ds_write_b16_d16_hi v145, v197 offset:944
	v_fma_f32 v194, v126, v128, v32
	v_fma_f32 v195, v126, v129, v16
	v_fma_f32 v194, -v127, v129, v194
	v_fma_f32 v195, v127, v128, v195
	v_bfe_u32 v196, v194, 16, 1
	v_bfe_u32 v197, v195, 16, 1
	v_add3_u32 v196, v194, v196, s22
	v_add3_u32 v197, v195, v197, s22
	ds_write_b16_d16_hi v145, v196 offset:1088
	ds_write_b16_d16_hi v145, v197 offset:1216
	v_fma_f32 v128, v126, v194, v33
	v_fma_f32 v129, v126, v195, v17
	v_fma_f32 v128, -v127, v195, v128
	v_fma_f32 v129, v127, v194, v129
	v_bfe_u32 v196, v128, 16, 1
	v_bfe_u32 v197, v129, 16, 1
	v_add3_u32 v196, v128, v196, s22
	v_add3_u32 v197, v129, v197, s22
	ds_write_b16_d16_hi v145, v196 offset:1360
	ds_write_b16_d16_hi v145, v197 offset:1488
	v_fma_f32 v194, v126, v128, v34
	v_fma_f32 v195, v126, v129, v18
	v_fma_f32 v194, -v127, v129, v194
	v_fma_f32 v195, v127, v128, v195
	v_bfe_u32 v196, v194, 16, 1
	v_bfe_u32 v197, v195, 16, 1
	v_add3_u32 v196, v194, v196, s22
	v_add3_u32 v197, v195, v197, s22
	ds_write_b16_d16_hi v145, v196 offset:1632
	ds_write_b16_d16_hi v145, v197 offset:1760
	v_fma_f32 v128, v126, v194, v35
	v_fma_f32 v129, v126, v195, v19
	v_fma_f32 v128, -v127, v195, v128
	v_fma_f32 v129, v127, v194, v129
	v_bfe_u32 v196, v128, 16, 1
	v_bfe_u32 v197, v129, 16, 1
	v_add3_u32 v196, v128, v196, s22
	v_add3_u32 v197, v129, v197, s22
	ds_write_b16_d16_hi v145, v196 offset:1904
	ds_write_b16_d16_hi v145, v197 offset:2032
	v_fma_f32 v194, v126, v128, v52
	v_fma_f32 v195, v126, v129, v4
	v_fma_f32 v194, -v127, v129, v194
	v_fma_f32 v195, v127, v128, v195
	v_bfe_u32 v196, v194, 16, 1
	v_bfe_u32 v197, v195, 16, 1
	v_add3_u32 v196, v194, v196, s22
	v_add3_u32 v197, v195, v197, s22
	ds_write_b16_d16_hi v145, v196 offset:2176
	ds_write_b16_d16_hi v145, v197 offset:2304
	v_fma_f32 v128, v126, v194, v53
	v_fma_f32 v129, v126, v195, v5
	v_fma_f32 v128, -v127, v195, v128
	v_fma_f32 v129, v127, v194, v129
	v_bfe_u32 v196, v128, 16, 1
	v_bfe_u32 v197, v129, 16, 1
	v_add3_u32 v196, v128, v196, s22
	v_add3_u32 v197, v129, v197, s22
	ds_write_b16_d16_hi v145, v196 offset:2448
; DI bf16_t f2bf(float x) { unsigned u = __float_as_uint(x); u += 0x7fffu + ((u >> 16) & 1u); return (bf16_t)(u >> 16); }
; template <bool PASS2>
; DI void s5_item(const Params& p, int l, int item, int lane, const bf16_t* ubuf, bf16_t* ybpre, bf16_t* xs, float* bus) {
;     ...
;       for (int t = 0; t < 16; t++) {
;         const float bur = bus[lane * 17 + t], bui = bus[(64 + lane) * 17 + t];
;         const float nxr = ar * xr - ai * xi + bur, nxi = ar * xi + ai * xr + bui;
;         xr = nxr; xi = nxi;
;         if (PASS2) {
;           xs[(half * 16 + t) * XSP + lane] = f2bf(xr);
;           xs[(half * 16 + t) * XSP + 64 + lane] = f2bf(xi);
;         }
;       }
	ds_write_b16_d16_hi v145, v197 offset:2576
	v_fma_f32 v194, v126, v128, v54
	v_fma_f32 v195, v126, v129, v6
	v_fma_f32 v194, -v127, v129, v194
	v_fma_f32 v195, v127, v128, v195
	v_bfe_u32 v196, v194, 16, 1
	v_bfe_u32 v197, v195, 16, 1
	v_add3_u32 v196, v194, v196, s22
	v_add3_u32 v197, v195, v197, s22
	ds_write_b16_d16_hi v145, v196 offset:2720
	ds_write_b16_d16_hi v145, v197 offset:2848
	v_fma_f32 v128, v126, v194, v55
	v_fma_f32 v129, v126, v195, v7
	v_fma_f32 v128, -v127, v195, v128
	v_fma_f32 v129, v127, v194, v129
	v_bfe_u32 v196, v128, 16, 1
	v_bfe_u32 v197, v129, 16, 1
	v_add3_u32 v196, v128, v196, s22
	v_add3_u32 v197, v129, v197, s22
	ds_write_b16_d16_hi v145, v196 offset:2992
	ds_write_b16_d16_hi v145, v197 offset:3120
	v_fma_f32 v194, v126, v128, v36
	v_fma_f32 v195, v126, v129, v20
	v_fma_f32 v194, -v127, v129, v194
	v_fma_f32 v195, v127, v128, v195
	v_bfe_u32 v196, v194, 16, 1
	v_bfe_u32 v197, v195, 16, 1
	v_add3_u32 v196, v194, v196, s22
	v_add3_u32 v197, v195, v197, s22
	ds_write_b16_d16_hi v145, v196 offset:3264
	ds_write_b16_d16_hi v145, v197 offset:3392
	v_fma_f32 v128, v126, v194, v37
	v_fma_f32 v129, v126, v195, v21
	v_fma_f32 v128, -v127, v195, v128
	v_fma_f32 v129, v127, v194, v129
	v_bfe_u32 v196, v128, 16, 1
	v_bfe_u32 v197, v129, 16, 1
	v_add3_u32 v196, v128, v196, s22
	v_add3_u32 v197, v129, v197, s22
	ds_write_b16_d16_hi v145, v196 offset:3536
	ds_write_b16_d16_hi v145, v197 offset:3664
	v_fma_f32 v194, v126, v128, v38
	v_fma_f32 v195, v126, v129, v22
	v_fma_f32 v194, -v127, v129, v194
	v_fma_f32 v195, v127, v128, v195
	v_bfe_u32 v196, v194, 16, 1
	v_bfe_u32 v197, v195, 16, 1
	v_add3_u32 v196, v194, v196, s22
	v_add3_u32 v197, v195, v197, s22
	ds_write_b16_d16_hi v145, v196 offset:3808
	ds_write_b16_d16_hi v145, v197 offset:3936
	v_fma_f32 v128, v126, v194, v39
	v_fma_f32 v129, v126, v195, v23
	v_fma_f32 v128, -v127, v195, v128
	v_fma_f32 v129, v127, v194, v129
	v_bfe_u32 v196, v128, 16, 1
	v_bfe_u32 v197, v129, 16, 1
	v_add3_u32 v196, v128, v196, s22
	v_add3_u32 v197, v129, v197, s22
	ds_write_b16_d16_hi v145, v196 offset:4080
	ds_write_b16_d16_hi v145, v197 offset:4208
	v_fma_f32 v194, v126, v128, v56
	v_fma_f32 v195, v126, v129, v8
	v_fma_f32 v194, -v127, v129, v194
	v_fma_f32 v195, v127, v128, v195
	v_bfe_u32 v196, v194, 16, 1
	v_bfe_u32 v197, v195, 16, 1
	v_add3_u32 v196, v194, v196, s22
	v_add3_u32 v197, v195, v197, s22
	ds_write_b16_d16_hi v145, v196 offset:4352
	ds_write_b16_d16_hi v145, v197 offset:4480
	v_fma_f32 v128, v126, v194, v57
	v_fma_f32 v129, v126, v195, v9
	v_fma_f32 v128, -v127, v195, v128
	v_fma_f32 v129, v127, v194, v129
	v_bfe_u32 v196, v128, 16, 1
	v_bfe_u32 v197, v129, 16, 1
	v_add3_u32 v196, v128, v196, s22
	v_add3_u32 v197, v129, v197, s22
	ds_write_b16_d16_hi v145, v196 offset:4624
	ds_write_b16_d16_hi v145, v197 offset:4752
	v_fma_f32 v194, v126, v128, v58
	v_fma_f32 v195, v126, v129, v10
	v_fma_f32 v194, -v127, v129, v194
	v_fma_f32 v195, v127, v128, v195
	v_bfe_u32 v196, v194, 16, 1
	v_bfe_u32 v197, v195, 16, 1
	v_add3_u32 v196, v194, v196, s22
	v_add3_u32 v197, v195, v197, s22
	ds_write_b16_d16_hi v145, v196 offset:4896
	ds_write_b16_d16_hi v145, v197 offset:5024
	v_fma_f32 v128, v126, v194, v59
	v_fma_f32 v129, v126, v195, v11
	v_fma_f32 v128, -v127, v195, v128
	v_fma_f32 v129, v127, v194, v129
	v_bfe_u32 v196, v128, 16, 1
	v_bfe_u32 v197, v129, 16, 1
	v_add3_u32 v196, v128, v196, s22
	v_add3_u32 v197, v129, v197, s22
	ds_write_b16_d16_hi v145, v196 offset:5168
	ds_write_b16_d16_hi v145, v197 offset:5296
	v_fma_f32 v194, v126, v128, v40
	v_fma_f32 v195, v126, v129, v24
	v_fma_f32 v194, -v127, v129, v194
	v_fma_f32 v195, v127, v128, v195
	v_bfe_u32 v196, v194, 16, 1
	v_bfe_u32 v197, v195, 16, 1
	v_add3_u32 v196, v194, v196, s22
	v_add3_u32 v197, v195, v197, s22
	ds_write_b16_d16_hi v145, v196 offset:5440
	ds_write_b16_d16_hi v145, v197 offset:5568
	v_fma_f32 v128, v126, v194, v41
	v_fma_f32 v129, v126, v195, v25
	v_fma_f32 v128, -v127, v195, v128
	v_fma_f32 v129, v127, v194, v129
	v_bfe_u32 v196, v128, 16, 1
	v_bfe_u32 v197, v129, 16, 1
	v_add3_u32 v196, v128, v196, s22
	v_add3_u32 v197, v129, v197, s22
	ds_write_b16_d16_hi v145, v196 offset:5712
	ds_write_b16_d16_hi v145, v197 offset:5840
	v_fma_f32 v194, v126, v128, v42
	v_fma_f32 v195, v126, v129, v26
	v_fma_f32 v194, -v127, v129, v194
	v_fma_f32 v195, v127, v128, v195
	v_bfe_u32 v196, v194, 16, 1
	v_bfe_u32 v197, v195, 16, 1
	v_add3_u32 v196, v194, v196, s22
	v_add3_u32 v197, v195, v197, s22
	ds_write_b16_d16_hi v145, v196 offset:5984
	ds_write_b16_d16_hi v145, v197 offset:6112
	v_fma_f32 v128, v126, v194, v43
	v_fma_f32 v129, v126, v195, v27
	v_fma_f32 v128, -v127, v195, v128
	v_fma_f32 v129, v127, v194, v129
	v_bfe_u32 v196, v128, 16, 1
	v_bfe_u32 v197, v129, 16, 1
	v_add3_u32 v196, v128, v196, s22
	v_add3_u32 v197, v129, v197, s22
	ds_write_b16_d16_hi v145, v196 offset:6256
	ds_write_b16_d16_hi v145, v197 offset:6384
	v_fma_f32 v194, v126, v128, v60
	v_fma_f32 v195, v126, v129, v12
	v_fma_f32 v194, -v127, v129, v194
	v_fma_f32 v195, v127, v128, v195
	v_bfe_u32 v196, v194, 16, 1
	v_bfe_u32 v197, v195, 16, 1
	v_add3_u32 v196, v194, v196, s22
	v_add3_u32 v197, v195, v197, s22
	ds_write_b16_d16_hi v145, v196 offset:6528
	ds_write_b16_d16_hi v145, v197 offset:6656
	v_fma_f32 v128, v126, v194, v61
	v_fma_f32 v129, v126, v195, v13
	v_fma_f32 v128, -v127, v195, v128
	v_fma_f32 v129, v127, v194, v129
	v_bfe_u32 v196, v128, 16, 1
	v_bfe_u32 v197, v129, 16, 1
	v_add3_u32 v196, v128, v196, s22
	v_add3_u32 v197, v129, v197, s22
	ds_write_b16_d16_hi v145, v196 offset:6800
	ds_write_b16_d16_hi v145, v197 offset:6928
; DI bf16_t f2bf(float x) { unsigned u = __float_as_uint(x); u += 0x7fffu + ((u >> 16) & 1u); return (bf16_t)(u >> 16); }
; template <bool PASS2>
; DI void s5_item(const Params& p, int l, int item, int lane, const bf16_t* ubuf, bf16_t* ybpre, bf16_t* xs, float* bus) {
;     ...
;       for (int t = 0; t < 16; t++) {
;         const float bur = bus[lane * 17 + t], bui = bus[(64 + lane) * 17 + t];
;         const float nxr = ar * xr - ai * xi + bur, nxi = ar * xi + ai * xr + bui;
;         xr = nxr; xi = nxi;
;         if (PASS2) {
;           xs[(half * 16 + t) * XSP + lane] = f2bf(xr);
;           xs[(half * 16 + t) * XSP + 64 + lane] = f2bf(xi);
;         }
;       }
;     }
;     if (PASS2) {
;       __builtin_amdgcn_fence(__ATOMIC_RELEASE, "wavefront");
;       __builtin_amdgcn_wave_barrier();
;       __builtin_amdgcn_fence(__ATOMIC_ACQUIRE, "wavefront");
;       f32x16 acc;
; #pragma unroll
;       for (int i = 0; i < 16; i++) acc[i] = 0.f;
; #pragma unroll
;       for (int ks = 0; ks < 8; ks++) {
;         const bf16x8 xf = *(const bf16x8*)(xs + r * XSP + ks * 16 + hh * 8);
;         acc = __builtin_amdgcn_mfma_f32_32x32x16_bf16(cf[ks], xf, acc, 0, 0, 0);
	v_fma_f32 v194, v126, v128, v62
	v_fma_f32 v195, v126, v129, v14
	v_fma_f32 v194, -v127, v129, v194
	v_fma_f32 v195, v127, v128, v195
	v_bfe_u32 v196, v194, 16, 1
	v_bfe_u32 v197, v195, 16, 1
	v_add3_u32 v196, v194, v196, s22
	v_add3_u32 v197, v195, v197, s22
	ds_write_b16_d16_hi v145, v196 offset:7072
	ds_write_b16_d16_hi v145, v197 offset:7200
	v_fma_f32 v128, v126, v194, v63
	v_fma_f32 v129, v126, v195, v15
	v_fma_f32 v128, -v127, v195, v128
	v_fma_f32 v129, v127, v194, v129
	v_bfe_u32 v196, v128, 16, 1
	v_bfe_u32 v197, v129, 16, 1
	v_add3_u32 v196, v128, v196, s22
	v_add3_u32 v197, v129, v197, s22
	ds_write_b16_d16_hi v145, v196 offset:7344
	ds_write_b16_d16_hi v145, v197 offset:7472
	v_fma_f32 v194, v126, v128, v44
	v_fma_f32 v195, v126, v129, v28
	v_fma_f32 v194, -v127, v129, v194
	v_fma_f32 v195, v127, v128, v195
	v_bfe_u32 v196, v194, 16, 1
	v_bfe_u32 v197, v195, 16, 1
	v_add3_u32 v196, v194, v196, s22
	v_add3_u32 v197, v195, v197, s22
	ds_write_b16_d16_hi v145, v196 offset:7616
	ds_write_b16_d16_hi v145, v197 offset:7744
	v_fma_f32 v128, v126, v194, v45
	v_fma_f32 v129, v126, v195, v29
	v_fma_f32 v128, -v127, v195, v128
	v_fma_f32 v129, v127, v194, v129
	v_bfe_u32 v196, v128, 16, 1
	v_bfe_u32 v197, v129, 16, 1
	v_add3_u32 v196, v128, v196, s22
	v_add3_u32 v197, v129, v197, s22
	ds_write_b16_d16_hi v145, v196 offset:7888
	ds_write_b16_d16_hi v145, v197 offset:8016
	v_fma_f32 v194, v126, v128, v46
	v_fma_f32 v195, v126, v129, v30
	v_fma_f32 v194, -v127, v129, v194
	v_fma_f32 v195, v127, v128, v195
	v_bfe_u32 v196, v194, 16, 1
	v_bfe_u32 v197, v195, 16, 1
	v_add3_u32 v196, v194, v196, s22
	v_add3_u32 v197, v195, v197, s22
	ds_write_b16_d16_hi v145, v196 offset:8160
	ds_write_b16_d16_hi v145, v197 offset:8288
	v_fma_f32 v128, v126, v194, v47
	v_fma_f32 v129, v126, v195, v31
	v_fma_f32 v128, -v127, v195, v128
	v_fma_f32 v129, v127, v194, v129
	v_bfe_u32 v196, v128, 16, 1
	v_bfe_u32 v197, v129, 16, 1
	v_add3_u32 v196, v128, v196, s22
	v_add3_u32 v197, v129, v197, s22
	ds_write_b16_d16_hi v145, v196 offset:8432
	ds_write_b16_d16_hi v145, v197 offset:8560
	ds_read_b128 v[0:3], v143
	ds_read_b128 v[16:19], v143 offset:32
	v_mov_b32_e32 v125, v115
	s_waitcnt lgkmcnt(1)
	v_mfma_f32_32x32x16_bf16 v[0:15], v[80:83], v[0:3], 0
	s_add_i32 s2, s10, 32
	s_cmpk_gt_u32 s10, 0x5f
	s_mov_b32 s10, s2
	s_waitcnt lgkmcnt(0)
	v_mfma_f32_32x32x16_bf16 v[0:15], v[84:87], v[16:19], v[0:15]
	ds_read_b128 v[16:19], v143 offset:64
	s_waitcnt lgkmcnt(0)
	v_mfma_f32_32x32x16_bf16 v[0:15], v[88:91], v[16:19], v[0:15]
	ds_read_b128 v[16:19], v143 offset:96
	s_waitcnt lgkmcnt(0)
	v_mfma_f32_32x32x16_bf16 v[0:15], v[92:95], v[16:19], v[0:15]
	ds_read_b128 v[16:19], v143 offset:128
	s_waitcnt lgkmcnt(0)
	v_mfma_f32_32x32x16_bf16 v[0:15], v[96:99], v[16:19], v[0:15]
	ds_read_b128 v[16:19], v143 offset:160
	s_waitcnt lgkmcnt(0)
	v_mfma_f32_32x32x16_bf16 v[0:15], v[100:103], v[16:19], v[0:15]
	ds_read_b128 v[16:19], v143 offset:192
	s_waitcnt lgkmcnt(0)
	v_mfma_f32_32x32x16_bf16 v[0:15], v[104:107], v[16:19], v[0:15]
	ds_read_b128 v[16:19], v143 offset:224
	s_waitcnt lgkmcnt(0)
	v_mfma_f32_32x32x16_bf16 v[0:15], v[108:111], v[16:19], v[0:15]
	s_nop 11
	v_lshl_add_u64 v[10:11], v[138:139], 0, v[124:125]
	v_mov_b32_e32 v23, v2
	v_mov_b32_e32 v2, v1
	v_mov_b32_e32 v22, v0
	v_lshl_add_u64 v[8:9], v[140:141], 1, v[136:137]
	s_waitcnt vmcnt(2)
; DI bf16_t f2bf(float x) { unsigned u = __float_as_uint(x); u += 0x7fffu + ((u >> 16) & 1u); return (bf16_t)(u >> 16); }
; DI float bf2f(bf16_t b) { return __uint_as_float(((unsigned)b) << 16); }
; template <bool PASS2>
; DI void s5_item(const Params& p, int l, int item, int lane, const bf16_t* ubuf, bf16_t* ybpre, bf16_t* xs, float* bus) {
;     ...
;       const size_t tok = tok0 + tb + r;
; #pragma unroll
;       for (int q = 0; q < 2; q++) {
;         const int c0 = 8 * q + 4 * hh;
;         const uint2 uu = *(const uint2*)(ubuf + tok * 512 + g * 16 + c0);
;         const float4 dd = *(const float4*)(p.in[I_S5_D] + l * 512 + g * 16 + c0);
;         const float u0 = bf2f((bf16_t)(uu.x & 0xffff)), u1 = bf2f((bf16_t)(uu.x >> 16));
;         const float u2 = bf2f((bf16_t)(uu.y & 0xffff)), u3 = bf2f((bf16_t)(uu.y >> 16));
;         const float o0 = gelu_tanh(acc[4 * q + 0] + dd.x * u0), o1 = gelu_tanh(acc[4 * q + 1] + dd.y * u1);
;         const float o2 = gelu_tanh(acc[4 * q + 2] + dd.z * u2), o3 = gelu_tanh(acc[4 * q + 3] + dd.w * u3);
;         uint2 pk;
;         pk.x = (unsigned)f2bf(o0) | ((unsigned)f2bf(o1) << 16);
;         pk.y = (unsigned)f2bf(o2) | ((unsigned)f2bf(o3) << 16);
;         *(uint2*)(ybpre + tok * 512 + g * 16 + c0) = pk;
;       }
;     }
;   }
	v_mov_b32_e32 v16, v220
	v_mov_b32_e32 v17, v221
	v_lshlrev_b32_e32 v19, 16, v17
	v_lshlrev_b32_e32 v18, 16, v16
	v_and_b32_e32 v17, 0xffff0000, v17
	v_and_b32_e32 v16, 0xffff0000, v16
	v_mov_b32_e32 v12, v212
	v_mov_b32_e32 v13, v213
	v_mov_b32_e32 v14, v214
	v_mov_b32_e32 v15, v215
	v_mov_b32_e32 v21, v14
	v_mov_b32_e32 v14, v13
	v_pk_fma_f32 v[2:3], v[14:15], v[16:17], v[2:3]
	v_mov_b32_e32 v20, v12
	v_mul_f32_e32 v1, 0x3d372713, v2
	v_mul_f32_e32 v1, v2, v1
	v_fma_f32 v1, v2, v1, v2
	v_mul_f32_e32 v1, 0x3f4c422a, v1
	v_add_f32_e32 v1, v1, v1
	v_mul_f32_e32 v1, 0x3fb8aa3b, v1
	v_exp_f32_e32 v1, v1
	v_pk_fma_f32 v[18:19], v[20:21], v[18:19], v[22:23]
	v_mul_f32_e32 v13, 0x3d372713, v3
	v_mul_f32_e32 v0, 0x3d372713, v18
	v_add_f32_e32 v1, 1.0, v1
	v_rcp_f32_e32 v12, v1
	v_mul_f32_e32 v1, 0x3d372713, v19
	v_mul_f32_e32 v0, v18, v0
	v_mul_f32_e32 v1, v19, v1
	v_fma_f32 v0, v18, v0, v18
	v_fma_f32 v1, v19, v1, v19
	v_mul_f32_e32 v13, v3, v13
	v_mul_f32_e32 v0, 0x3f4c422a, v0
	v_mul_f32_e32 v1, 0x3f4c422a, v1
	v_fma_f32 v13, v3, v13, v3
	v_add_f32_e32 v0, v0, v0
	v_add_f32_e32 v1, v1, v1
	v_mul_f32_e32 v13, 0x3f4c422a, v13
	v_mul_f32_e32 v0, 0x3fb8aa3b, v0
	v_mul_f32_e32 v1, 0x3fb8aa3b, v1
	v_add_f32_e32 v13, v13, v13
	v_exp_f32_e32 v0, v0
	v_exp_f32_e32 v1, v1
	v_mul_f32_e32 v13, 0x3fb8aa3b, v13
	v_exp_f32_e32 v13, v13
	v_add_f32_e32 v0, 1.0, v0
	v_add_f32_e32 v1, 1.0, v1
	v_rcp_f32_e32 v0, v0
	v_rcp_f32_e32 v1, v1
	v_add_f32_e32 v13, 1.0, v13
	v_rcp_f32_e32 v13, v13
	v_pk_mul_f32 v[14:15], v[18:19], 0.5 op_sel_hi:[1,0]
	v_pk_fma_f32 v[0:1], v[0:1], 2.0, 1.0 op_sel_hi:[1,0,0] neg_lo:[1,0,0] neg_hi:[1,0,0]
	v_pk_mul_f32 v[2:3], v[2:3], 0.5 op_sel_hi:[1,0]
	v_pk_add_f32 v[0:1], v[0:1], 1.0 op_sel_hi:[1,0]
	v_pk_fma_f32 v[12:13], v[12:13], 2.0, 1.0 op_sel_hi:[1,0,0] neg_lo:[1,0,0] neg_hi:[1,0,0]
	v_pk_mul_f32 v[0:1], v[14:15], v[0:1]
	v_pk_add_f32 v[12:13], v[12:13], 1.0 op_sel_hi:[1,0]
	v_mov_b32_e32 v17, v6
	v_pk_mul_f32 v[2:3], v[2:3], v[12:13]
	v_and_b32_sdwa v12, v1, v180 dst_sel:DWORD dst_unused:UNUSED_PAD src0_sel:WORD_1 src1_sel:DWORD
	v_and_b32_sdwa v13, v0, v180 dst_sel:DWORD dst_unused:UNUSED_PAD src0_sel:WORD_1 src1_sel:DWORD
	v_add3_u32 v0, v0, v13, s22
	v_add3_u32 v1, v1, v12, s22
	v_and_b32_sdwa v12, v3, v180 dst_sel:DWORD dst_unused:UNUSED_PAD src0_sel:WORD_1 src1_sel:DWORD
	v_and_b32_sdwa v13, v2, v180 dst_sel:DWORD dst_unused:UNUSED_PAD src0_sel:WORD_1 src1_sel:DWORD
	v_add3_u32 v3, v3, v12, s22
	v_add3_u32 v2, v2, v13, s22
	v_and_b32_e32 v3, 0xffff0000, v3
	v_and_b32_e32 v2, 0xffff0000, v2
	v_or_b32_sdwa v1, v3, v1 dst_sel:DWORD dst_unused:UNUSED_PAD src0_sel:DWORD src1_sel:WORD_1
	v_or_b32_sdwa v0, v2, v0 dst_sel:DWORD dst_unused:UNUSED_PAD src0_sel:DWORD src1_sel:WORD_1
	global_store_dwordx2 v[8:9], v[0:1], off
	s_nop 0
	v_mov_b32_e32 v6, v5
	v_mov_b32_e32 v16, v4
	s_waitcnt vmcnt(2)
	v_mov_b32_e32 v0, v222
	v_mov_b32_e32 v1, v223
	v_lshlrev_b32_e32 v3, 16, v1
	v_lshlrev_b32_e32 v2, 16, v0
	v_and_b32_e32 v1, 0xffff0000, v1
	v_and_b32_e32 v0, 0xffff0000, v0
	v_mov_b32_e32 v10, v216
	v_mov_b32_e32 v11, v217
	v_mov_b32_e32 v12, v218
	v_mov_b32_e32 v13, v219
	v_mov_b32_e32 v15, v12
	v_mov_b32_e32 v12, v11
	v_pk_fma_f32 v[0:1], v[12:13], v[0:1], v[6:7]
	v_mov_b32_e32 v14, v10
	v_mul_f32_e32 v5, 0x3d372713, v0
	v_mul_f32_e32 v5, v0, v5
	v_fma_f32 v5, v0, v5, v0
	v_mul_f32_e32 v5, 0x3f4c422a, v5
	v_add_f32_e32 v5, v5, v5
	v_mul_f32_e32 v5, 0x3fb8aa3b, v5
	v_exp_f32_e32 v5, v5
	v_pk_fma_f32 v[2:3], v[14:15], v[2:3], v[16:17]
	v_add_f32_e32 v5, 1.0, v5
	v_mul_f32_e32 v4, 0x3d372713, v2
	v_rcp_f32_e32 v6, v5
	v_mul_f32_e32 v5, 0x3d372713, v3
	v_mul_f32_e32 v4, v2, v4
	v_mul_f32_e32 v5, v3, v5
	v_fma_f32 v4, v2, v4, v2
	v_fma_f32 v5, v3, v5, v3
	v_mul_f32_e32 v4, 0x3f4c422a, v4
	v_mul_f32_e32 v5, 0x3f4c422a, v5
	v_add_f32_e32 v4, v4, v4
	v_add_f32_e32 v5, v5, v5
	v_mul_f32_e32 v4, 0x3fb8aa3b, v4
	v_mul_f32_e32 v5, 0x3fb8aa3b, v5
	v_exp_f32_e32 v4, v4
	v_exp_f32_e32 v5, v5
	v_pk_mul_f32 v[2:3], v[2:3], 0.5 op_sel_hi:[1,0]
	v_add_f32_e32 v4, 1.0, v4
	v_add_f32_e32 v5, 1.0, v5
	v_rcp_f32_e32 v4, v4
	v_rcp_f32_e32 v5, v5
	s_nop 0
	v_pk_fma_f32 v[4:5], v[4:5], 2.0, 1.0 op_sel_hi:[1,0,0] neg_lo:[1,0,0] neg_hi:[1,0,0]
	s_nop 0
	v_pk_add_f32 v[4:5], v[4:5], 1.0 op_sel_hi:[1,0]
	s_nop 0
	v_pk_mul_f32 v[2:3], v[2:3], v[4:5]
	v_mul_f32_e32 v4, 0x3d372713, v1
	v_mul_f32_e32 v4, v1, v4
	v_fma_f32 v4, v1, v4, v1
	v_mul_f32_e32 v4, 0x3f4c422a, v4
	v_add_f32_e32 v4, v4, v4
	v_mul_f32_e32 v4, 0x3fb8aa3b, v4
	v_exp_f32_e32 v4, v4
	v_pk_mul_f32 v[0:1], v[0:1], 0.5 op_sel_hi:[1,0]
	v_add_f32_e32 v4, 1.0, v4
	v_rcp_f32_e32 v7, v4
	s_nop 0
	v_pk_fma_f32 v[4:5], v[6:7], 2.0, 1.0 op_sel_hi:[1,0,0] neg_lo:[1,0,0] neg_hi:[1,0,0]
	s_nop 0
	v_pk_add_f32 v[4:5], v[4:5], 1.0 op_sel_hi:[1,0]
	s_nop 0
	v_pk_mul_f32 v[0:1], v[0:1], v[4:5]
	v_and_b32_sdwa v4, v3, v180 dst_sel:DWORD dst_unused:UNUSED_PAD src0_sel:WORD_1 src1_sel:DWORD
	v_and_b32_sdwa v5, v2, v180 dst_sel:DWORD dst_unused:UNUSED_PAD src0_sel:WORD_1 src1_sel:DWORD
	v_add3_u32 v2, v2, v5, s22
	v_add3_u32 v3, v3, v4, s22
	v_and_b32_sdwa v4, v1, v180 dst_sel:DWORD dst_unused:UNUSED_PAD src0_sel:WORD_1 src1_sel:DWORD
	v_and_b32_sdwa v5, v0, v180 dst_sel:DWORD dst_unused:UNUSED_PAD src0_sel:WORD_1 src1_sel:DWORD
	v_add3_u32 v1, v1, v4, s22
	v_add3_u32 v0, v0, v5, s22
	v_and_b32_e32 v1, 0xffff0000, v1
	v_and_b32_e32 v0, 0xffff0000, v0
	v_or_b32_sdwa v1, v1, v3 dst_sel:DWORD dst_unused:UNUSED_PAD src0_sel:DWORD src1_sel:WORD_1
	v_or_b32_sdwa v0, v0, v2 dst_sel:DWORD dst_unused:UNUSED_PAD src0_sel:DWORD src1_sel:WORD_1
	global_store_dwordx2 v[8:9], v[0:1], off offset:16
	s_cbranch_scc0 .LBB0_786
	v_readlane_b32 s2, v252, 27
	v_readlane_b32 s3, v252, 28
	s_nop 0
	v_add_u32_e32 v142, s2, v142
	s_movk_i32 s2, 0x1fff
	v_cmp_lt_i32_e64 s[4:5], s2, v142
	s_or_b64 s[8:9], s[4:5], s[8:9]
	s_andn2_b64 exec, exec, s[8:9]
	s_cbranch_execnz .LBB0_659
	s_branch .LBB0_798

; DI bf16_t f2bf(float x) { unsigned u = __float_as_uint(x); u += 0x7fffu + ((u >> 16) & 1u); return (bf16_t)(u >> 16); }
; template <bool PASS2>
; DI void s5_item(const Params& p, int l, int item, int lane, const bf16_t* ubuf, bf16_t* ybpre, bf16_t* xs, float* bus) {
;     ...
;   for (int tb = 0; tb < LC5; tb += 32) {
;     const bf16x8 uf = *(const bf16x8*)(ubuf + (tok0 + tb + r) * 512 + g * 16 + 8 * hh);
;     f32x16 D[4];
; #pragma unroll
;     for (int mt = 0; mt < 4; mt++) {
; #pragma unroll
;       for (int i = 0; i < 16; i++) D[mt][i] = 0.f;
;       D[mt] = __builtin_amdgcn_mfma_f32_32x32x16_bf16(bf_[mt], uf, D[mt], 0, 0, 0);
;     }
; #pragma unroll
;     for (int half = 0; half < 2; half++) {
;       __builtin_amdgcn_fence(__ATOMIC_RELEASE, "wavefront");
;       __builtin_amdgcn_wave_barrier();
;       if ((r >> 4) == half) {
; #pragma unroll
;         for (int mt = 0; mt < 4; mt++)
; #pragma unroll
;           for (int i = 0; i < 16; i++)
;             bus[(32 * mt + (i & 3) + 8 * (i >> 2) + 4 * hh) * 17 + (r & 15)] = D[mt][i];
;       }
;       __builtin_amdgcn_fence(__ATOMIC_RELEASE, "wavefront");
;       __builtin_amdgcn_wave_barrier();
;       __builtin_amdgcn_fence(__ATOMIC_ACQUIRE, "wavefront");
; #pragma unroll 4
;       for (int t = 0; t < 16; t++) {
;         const float bur = bus[lane * 17 + t], bui = bus[(64 + lane) * 17 + t];
;         const float nxr = ar * xr - ai * xi + bur, nxi = ar * xi + ai * xr + bui;
;         xr = nxr; xi = nxi;
;         if (PASS2) {
;           xs[(half * 16 + t) * XSP + lane] = f2bf(xr);
;           xs[(half * 16 + t) * XSP + 64 + lane] = f2bf(xi);
;         }
;       }
;     }
;     ...
;   if (!PASS2) { st[0] = xr; st[1] = xi; }
.LBB0_2400:
	v_lshl_add_u64 v[0:1], v[92:93], 0, s[14:15]
	v_lshlrev_b64 v[0:1], 10, v[0:1]
	v_lshl_add_u64 v[0:1], v[90:91], 0, v[0:1]
	global_load_dwordx4 v[0:3], v[0:1], off
	s_waitcnt vmcnt(0)
	v_mov_b32_e32 v114, v0
	v_mov_b32_e32 v115, v1
	v_mov_b32_e32 v116, v2
	v_mov_b32_e32 v117, v3
	s_nop 1
	v_mfma_f32_32x32x16_bf16 v[48:63], v[114:117], v[64:67], 0
	v_mfma_f32_32x32x16_bf16 v[32:47], v[114:117], v[68:71], 0
	v_mfma_f32_32x32x16_bf16 v[16:31], v[114:117], v[72:75], 0
	v_mfma_f32_32x32x16_bf16 v[0:15], v[114:117], v[76:79], 0
	s_nop 7
	s_nop 3
	v_permlane32_swap_b32 v48, v32
	v_permlane32_swap_b32 v49, v33
	v_permlane32_swap_b32 v50, v34
	v_permlane32_swap_b32 v51, v35
	v_permlane32_swap_b32 v52, v36
	v_permlane32_swap_b32 v53, v37
	v_permlane32_swap_b32 v54, v38
	v_permlane32_swap_b32 v55, v39
	v_permlane32_swap_b32 v56, v40
	v_permlane32_swap_b32 v57, v41
	v_permlane32_swap_b32 v58, v42
	v_permlane32_swap_b32 v59, v43
	v_permlane32_swap_b32 v60, v44
	v_permlane32_swap_b32 v61, v45
	v_permlane32_swap_b32 v62, v46
	v_permlane32_swap_b32 v63, v47
	v_permlane32_swap_b32 v16, v0
	v_permlane32_swap_b32 v17, v1
	v_permlane32_swap_b32 v18, v2
	v_permlane32_swap_b32 v19, v3
	v_permlane32_swap_b32 v20, v4
	v_permlane32_swap_b32 v21, v5
	v_permlane32_swap_b32 v22, v6
	v_permlane32_swap_b32 v23, v7
	v_permlane32_swap_b32 v24, v8
	v_permlane32_swap_b32 v25, v9
	v_permlane32_swap_b32 v26, v10
	v_permlane32_swap_b32 v27, v11
	v_permlane32_swap_b32 v28, v12
	v_permlane32_swap_b32 v29, v13
	v_permlane32_swap_b32 v30, v14
	v_permlane32_swap_b32 v31, v15
	v_fma_f32 v112, v88, v96, v48
	v_fma_f32 v113, v88, v98, v16
	v_fma_f32 v112, -v89, v98, v112
	v_fma_f32 v113, v89, v96, v113
	v_fma_f32 v96, v88, v112, v49
	v_fma_f32 v98, v88, v113, v17
	v_fma_f32 v96, -v89, v113, v96
	v_fma_f32 v98, v89, v112, v98
	v_fma_f32 v112, v88, v96, v50
	v_fma_f32 v113, v88, v98, v18
	v_fma_f32 v112, -v89, v98, v112
	v_fma_f32 v113, v89, v96, v113
	v_fma_f32 v96, v88, v112, v51
	v_fma_f32 v98, v88, v113, v19
	v_fma_f32 v96, -v89, v113, v96
	v_fma_f32 v98, v89, v112, v98
	v_fma_f32 v112, v88, v96, v32
	v_fma_f32 v113, v88, v98, v0
	v_fma_f32 v112, -v89, v98, v112
	v_fma_f32 v113, v89, v96, v113
	v_fma_f32 v96, v88, v112, v33
	v_fma_f32 v98, v88, v113, v1
	v_fma_f32 v96, -v89, v113, v96
	v_fma_f32 v98, v89, v112, v98
	v_fma_f32 v112, v88, v96, v34
	v_fma_f32 v113, v88, v98, v2
	v_fma_f32 v112, -v89, v98, v112
	v_fma_f32 v113, v89, v96, v113
	v_fma_f32 v96, v88, v112, v35
	v_fma_f32 v98, v88, v113, v3
	v_fma_f32 v96, -v89, v113, v96
	v_fma_f32 v98, v89, v112, v98
	v_fma_f32 v112, v88, v96, v52
	v_fma_f32 v113, v88, v98, v20
	v_fma_f32 v112, -v89, v98, v112
	v_fma_f32 v113, v89, v96, v113
	v_fma_f32 v96, v88, v112, v53
	v_fma_f32 v98, v88, v113, v21
	v_fma_f32 v96, -v89, v113, v96
	v_fma_f32 v98, v89, v112, v98
	v_fma_f32 v112, v88, v96, v54
	v_fma_f32 v113, v88, v98, v22
	v_fma_f32 v112, -v89, v98, v112
	v_fma_f32 v113, v89, v96, v113
	v_fma_f32 v96, v88, v112, v55
	v_fma_f32 v98, v88, v113, v23
	v_fma_f32 v96, -v89, v113, v96
	v_fma_f32 v98, v89, v112, v98
	v_fma_f32 v112, v88, v96, v36
	v_fma_f32 v113, v88, v98, v4
	v_fma_f32 v112, -v89, v98, v112
	v_fma_f32 v113, v89, v96, v113
	v_fma_f32 v96, v88, v112, v37
	v_fma_f32 v98, v88, v113, v5
	v_fma_f32 v96, -v89, v113, v96
	v_fma_f32 v98, v89, v112, v98
	v_fma_f32 v112, v88, v96, v38
	v_fma_f32 v113, v88, v98, v6
	v_fma_f32 v112, -v89, v98, v112
	v_fma_f32 v113, v89, v96, v113
	v_fma_f32 v96, v88, v112, v39
	v_fma_f32 v98, v88, v113, v7
	v_fma_f32 v96, -v89, v113, v96
	v_fma_f32 v98, v89, v112, v98
	v_fma_f32 v112, v88, v96, v56
	v_fma_f32 v113, v88, v98, v24
	v_fma_f32 v112, -v89, v98, v112
	v_fma_f32 v113, v89, v96, v113
	v_fma_f32 v96, v88, v112, v57
	v_fma_f32 v98, v88, v113, v25
	v_fma_f32 v96, -v89, v113, v96
	v_fma_f32 v98, v89, v112, v98
	v_fma_f32 v112, v88, v96, v58
	v_fma_f32 v113, v88, v98, v26
	v_fma_f32 v112, -v89, v98, v112
	v_fma_f32 v113, v89, v96, v113
	v_fma_f32 v96, v88, v112, v59
	v_fma_f32 v98, v88, v113, v27
	v_fma_f32 v96, -v89, v113, v96
	v_fma_f32 v98, v89, v112, v98
	v_fma_f32 v112, v88, v96, v40
	v_fma_f32 v113, v88, v98, v8
	v_fma_f32 v112, -v89, v98, v112
	v_fma_f32 v113, v89, v96, v113
	v_fma_f32 v96, v88, v112, v41
	v_fma_f32 v98, v88, v113, v9
	v_fma_f32 v96, -v89, v113, v96
	v_fma_f32 v98, v89, v112, v98
	v_fma_f32 v112, v88, v96, v42
	v_fma_f32 v113, v88, v98, v10
	v_fma_f32 v112, -v89, v98, v112
	v_fma_f32 v113, v89, v96, v113
	v_fma_f32 v96, v88, v112, v43
	v_fma_f32 v98, v88, v113, v11
	v_fma_f32 v96, -v89, v113, v96
	v_fma_f32 v98, v89, v112, v98
	v_fma_f32 v112, v88, v96, v60
	v_fma_f32 v113, v88, v98, v28
	v_fma_f32 v112, -v89, v98, v112
	v_fma_f32 v113, v89, v96, v113
	v_fma_f32 v96, v88, v112, v61
	v_fma_f32 v98, v88, v113, v29
	v_fma_f32 v96, -v89, v113, v96
	v_fma_f32 v98, v89, v112, v98
	v_fma_f32 v112, v88, v96, v62
	v_fma_f32 v113, v88, v98, v30
	v_fma_f32 v112, -v89, v98, v112
	v_fma_f32 v113, v89, v96, v113
	v_fma_f32 v96, v88, v112, v63
	v_fma_f32 v98, v88, v113, v31
	v_fma_f32 v96, -v89, v113, v96
	v_fma_f32 v98, v89, v112, v98
	v_fma_f32 v112, v88, v96, v44
	v_fma_f32 v113, v88, v98, v12
	v_fma_f32 v112, -v89, v98, v112
	v_fma_f32 v113, v89, v96, v113
	v_fma_f32 v96, v88, v112, v45
	v_fma_f32 v98, v88, v113, v13
	v_fma_f32 v96, -v89, v113, v96
	v_fma_f32 v98, v89, v112, v98
	v_fma_f32 v112, v88, v96, v46
	v_fma_f32 v113, v88, v98, v14
	v_fma_f32 v112, -v89, v98, v112
	v_fma_f32 v113, v89, v96, v113
	v_fma_f32 v96, v88, v112, v47
	v_fma_f32 v98, v88, v113, v15
	v_fma_f32 v96, -v89, v113, v96
	v_fma_f32 v98, v89, v112, v98
	v_mov_b32_e32 v97, v98
	s_add_i32 s1, s14, 32
	s_cmpk_gt_u32 s14, 0x5f
	v_mov_b32_e32 v98, v97
	s_mov_b32 s14, s1
	s_cbranch_scc0 .LBB0_2400
	s_lshl_b32 s0, s0, 12
	s_lshl_b32 s1, s6, 7
	s_add_i32 s0, s0, s18
	s_add_i32 s0, s0, s1
	s_ashr_i32 s1, s0, 31
	s_lshl_b64 s[0:1], s[0:1], 9
	v_lshl_add_u64 v[0:1], v[84:85], 0, s[0:1]
	v_readlane_b32 s0, v252, 27
	v_readlane_b32 s1, v252, 28
	global_store_dwordx2 v[0:1], v[96:97], off
	v_add_u32_e32 v99, s0, v99
	s_movk_i32 s0, 0x1fff
	v_cmp_lt_i32_e64 s[0:1], s0, v99
	s_or_b64 s[12:13], s[0:1], s[12:13]
	s_andn2_b64 exec, exec, s[12:13]
	s_cbranch_execnz .LBB0_2399

; DI bf16_t f2bf(float x) { unsigned u = __float_as_uint(x); u += 0x7fffu + ((u >> 16) & 1u); return (bf16_t)(u >> 16); }
; template <bool PASS2>
; DI void s5_item(const Params& p, int l, int item, int lane, const bf16_t* ubuf, bf16_t* ybpre, bf16_t* xs, float* bus) {
;     ...
;     const bf16x8 uf = *(const bf16x8*)(ubuf + (tok0 + tb + r) * 512 + g * 16 + 8 * hh);
;     f32x16 D[4];
; #pragma unroll
;     for (int mt = 0; mt < 4; mt++) {
; #pragma unroll
;       for (int i = 0; i < 16; i++) D[mt][i] = 0.f;
;       D[mt] = __builtin_amdgcn_mfma_f32_32x32x16_bf16(bf_[mt], uf, D[mt], 0, 0, 0);
;     }
; #pragma unroll
;     for (int half = 0; half < 2; half++) {
;       __builtin_amdgcn_fence(__ATOMIC_RELEASE, "wavefront");
;       __builtin_amdgcn_wave_barrier();
;       if ((r >> 4) == half) {
; #pragma unroll
;         for (int mt = 0; mt < 4; mt++)
; #pragma unroll
;           for (int i = 0; i < 16; i++)
;             bus[(32 * mt + (i & 3) + 8 * (i >> 2) + 4 * hh) * 17 + (r & 15)] = D[mt][i];
;       }
;       __builtin_amdgcn_fence(__ATOMIC_RELEASE, "wavefront");
;       __builtin_amdgcn_wave_barrier();
;       __builtin_amdgcn_fence(__ATOMIC_ACQUIRE, "wavefront");
; #pragma unroll 4
;       for (int t = 0; t < 16; t++) {
;         const float bur = bus[lane * 17 + t], bui = bus[(64 + lane) * 17 + t];
;         const float nxr = ar * xr - ai * xi + bur, nxi = ar * xi + ai * xr + bui;
;         xr = nxr; xi = nxi;
;         if (PASS2) {
;           xs[(half * 16 + t) * XSP + lane] = f2bf(xr);
;           xs[(half * 16 + t) * XSP + 64 + lane] = f2bf(xi);
;         }
;       }
.LBB0_2662:
	v_lshl_add_u64 v[140:141], v[130:131], 0, s[14:15]
	v_lshlrev_b64 v[0:1], 10, v[140:141]
	v_lshl_add_u64 v[138:139], s[0:1], 0, v[0:1]
	v_lshl_add_u64 v[0:1], v[138:139], 0, v[114:115]
	v_lshl_add_u64 v[208:209], v[0:1], 0, s[98:99]
	v_mov_b32_e32 v206, v124
	v_mov_b32_e32 v207, v115
	v_lshl_add_u64 v[206:207], v[138:139], 0, v[206:207]
	global_load_dwordx2 v[220:221], v[206:207], off
	global_load_dwordx2 v[222:223], v[206:207], off offset:16
	v_add_u32_e32 v190, 0x8800, v144
	v_add_u32_e32 v189, 0x8c00, v144
	v_add_u32_e32 v187, 0x9000, v144
	v_add_u32_e32 v188, 0x9400, v144
	v_add_u32_e32 v186, 0x9800, v144
	v_add_u32_e32 v184, 0x9c00, v144
	v_add_u32_e32 v185, 0x9e00, v144
	v_add_u32_e32 v183, 0xa000, v144
	v_add_u32_e32 v125, 0xa400, v144
	v_add_u32_e32 v181, 0xa600, v144
	v_add_u32_e32 v182, 0xa800, v144
	s_waitcnt vmcnt(4)
	v_mfma_f32_32x32x16_bf16 v[48:63], v[202:205], v[64:67], 0
	v_mfma_f32_32x32x16_bf16 v[32:47], v[202:205], v[68:71], 0
	v_mfma_f32_32x32x16_bf16 v[0:15], v[202:205], v[72:75], 0
	v_mfma_f32_32x32x16_bf16 v[16:31], v[202:205], v[76:79], 0
	global_load_dwordx4 v[202:205], v[208:209], off
	v_lshlrev_b64 v[140:141], 9, v[140:141]
	s_nop 7
	s_nop 1
	v_permlane32_swap_b32 v48, v32
	v_permlane32_swap_b32 v49, v33
	v_permlane32_swap_b32 v50, v34
	v_permlane32_swap_b32 v51, v35
	v_permlane32_swap_b32 v52, v36
	v_permlane32_swap_b32 v53, v37
	v_permlane32_swap_b32 v54, v38
	v_permlane32_swap_b32 v55, v39
	v_permlane32_swap_b32 v56, v40
	v_permlane32_swap_b32 v57, v41
	v_permlane32_swap_b32 v58, v42
	v_permlane32_swap_b32 v59, v43
	v_permlane32_swap_b32 v60, v44
	v_permlane32_swap_b32 v61, v45
	v_permlane32_swap_b32 v62, v46
	v_permlane32_swap_b32 v63, v47
	v_permlane32_swap_b32 v0, v16
	v_permlane32_swap_b32 v1, v17
	v_permlane32_swap_b32 v2, v18
	v_permlane32_swap_b32 v3, v19
	v_permlane32_swap_b32 v4, v20
	v_permlane32_swap_b32 v5, v21
	v_permlane32_swap_b32 v6, v22
	v_permlane32_swap_b32 v7, v23
	v_permlane32_swap_b32 v8, v24
	v_permlane32_swap_b32 v9, v25
	v_permlane32_swap_b32 v10, v26
	v_permlane32_swap_b32 v11, v27
	v_permlane32_swap_b32 v12, v28
	v_permlane32_swap_b32 v13, v29
	v_permlane32_swap_b32 v14, v30
	v_permlane32_swap_b32 v15, v31
	v_fma_f32 v194, v126, v128, v48
	v_fma_f32 v195, v126, v129, v0
	v_fma_f32 v194, -v127, v129, v194
	v_fma_f32 v195, v127, v128, v195
	v_bfe_u32 v196, v194, 16, 1
	v_bfe_u32 v197, v195, 16, 1
	v_add3_u32 v196, v194, v196, s6
	v_add3_u32 v197, v195, v197, s6
	ds_write_b16_d16_hi v145, v196 offset:0
	ds_write_b16_d16_hi v145, v197 offset:128
	v_fma_f32 v128, v126, v194, v49
	v_fma_f32 v129, v126, v195, v1
	v_fma_f32 v128, -v127, v195, v128
	v_fma_f32 v129, v127, v194, v129
	v_bfe_u32 v196, v128, 16, 1
	v_bfe_u32 v197, v129, 16, 1
	v_add3_u32 v196, v128, v196, s6
	v_add3_u32 v197, v129, v197, s6
	ds_write_b16_d16_hi v145, v196 offset:272
	ds_write_b16_d16_hi v145, v197 offset:400
	v_fma_f32 v194, v126, v128, v50
	v_fma_f32 v195, v126, v129, v2
	v_fma_f32 v194, -v127, v129, v194
	v_fma_f32 v195, v127, v128, v195
	v_bfe_u32 v196, v194, 16, 1
	v_bfe_u32 v197, v195, 16, 1
	v_add3_u32 v196, v194, v196, s6
	v_add3_u32 v197, v195, v197, s6
	ds_write_b16_d16_hi v145, v196 offset:544
	ds_write_b16_d16_hi v145, v197 offset:672
	v_fma_f32 v128, v126, v194, v51
	v_fma_f32 v129, v126, v195, v3
	v_fma_f32 v128, -v127, v195, v128
	v_fma_f32 v129, v127, v194, v129
	v_bfe_u32 v196, v128, 16, 1
	v_bfe_u32 v197, v129, 16, 1
	v_add3_u32 v196, v128, v196, s6
	v_add3_u32 v197, v129, v197, s6
	ds_write_b16_d16_hi v145, v196 offset:816
	ds_write_b16_d16_hi v145, v197 offset:944
	v_fma_f32 v194, v126, v128, v32
	v_fma_f32 v195, v126, v129, v16
	v_fma_f32 v194, -v127, v129, v194
	v_fma_f32 v195, v127, v128, v195
	v_bfe_u32 v196, v194, 16, 1
	v_bfe_u32 v197, v195, 16, 1
	v_add3_u32 v196, v194, v196, s6
	v_add3_u32 v197, v195, v197, s6
	ds_write_b16_d16_hi v145, v196 offset:1088
	ds_write_b16_d16_hi v145, v197 offset:1216
	v_fma_f32 v128, v126, v194, v33
	v_fma_f32 v129, v126, v195, v17
	v_fma_f32 v128, -v127, v195, v128
	v_fma_f32 v129, v127, v194, v129
	v_bfe_u32 v196, v128, 16, 1
	v_bfe_u32 v197, v129, 16, 1
	v_add3_u32 v196, v128, v196, s6
	v_add3_u32 v197, v129, v197, s6
	ds_write_b16_d16_hi v145, v196 offset:1360
	ds_write_b16_d16_hi v145, v197 offset:1488
	v_fma_f32 v194, v126, v128, v34
	v_fma_f32 v195, v126, v129, v18
	v_fma_f32 v194, -v127, v129, v194
	v_fma_f32 v195, v127, v128, v195
	v_bfe_u32 v196, v194, 16, 1
	v_bfe_u32 v197, v195, 16, 1
	v_add3_u32 v196, v194, v196, s6
	v_add3_u32 v197, v195, v197, s6
	ds_write_b16_d16_hi v145, v196 offset:1632
	ds_write_b16_d16_hi v145, v197 offset:1760
	v_fma_f32 v128, v126, v194, v35
	v_fma_f32 v129, v126, v195, v19
	v_fma_f32 v128, -v127, v195, v128
	v_fma_f32 v129, v127, v194, v129
	v_bfe_u32 v196, v128, 16, 1
	v_bfe_u32 v197, v129, 16, 1
	v_add3_u32 v196, v128, v196, s6
	v_add3_u32 v197, v129, v197, s6
	ds_write_b16_d16_hi v145, v196 offset:1904
	ds_write_b16_d16_hi v145, v197 offset:2032
	v_fma_f32 v194, v126, v128, v52
	v_fma_f32 v195, v126, v129, v4
	v_fma_f32 v194, -v127, v129, v194
	v_fma_f32 v195, v127, v128, v195
	v_bfe_u32 v196, v194, 16, 1
	v_bfe_u32 v197, v195, 16, 1
	v_add3_u32 v196, v194, v196, s6
	v_add3_u32 v197, v195, v197, s6
	ds_write_b16_d16_hi v145, v196 offset:2176
	ds_write_b16_d16_hi v145, v197 offset:2304
	v_fma_f32 v128, v126, v194, v53
	v_fma_f32 v129, v126, v195, v5
	v_fma_f32 v128, -v127, v195, v128
	v_fma_f32 v129, v127, v194, v129
	v_bfe_u32 v196, v128, 16, 1
	v_bfe_u32 v197, v129, 16, 1
	v_add3_u32 v196, v128, v196, s6
	v_add3_u32 v197, v129, v197, s6
	ds_write_b16_d16_hi v145, v196 offset:2448
; DI bf16_t f2bf(float x) { unsigned u = __float_as_uint(x); u += 0x7fffu + ((u >> 16) & 1u); return (bf16_t)(u >> 16); }
; template <bool PASS2>
; DI void s5_item(const Params& p, int l, int item, int lane, const bf16_t* ubuf, bf16_t* ybpre, bf16_t* xs, float* bus) {
;     ...
; #pragma unroll 4
;       for (int t = 0; t < 16; t++) {
;         const float bur = bus[lane * 17 + t], bui = bus[(64 + lane) * 17 + t];
;         const float nxr = ar * xr - ai * xi + bur, nxi = ar * xi + ai * xr + bui;
;         xr = nxr; xi = nxi;
;         if (PASS2) {
;           xs[(half * 16 + t) * XSP + lane] = f2bf(xr);
;           xs[(half * 16 + t) * XSP + 64 + lane] = f2bf(xi);
;         }
;       }
	ds_write_b16_d16_hi v145, v197 offset:2576
	v_fma_f32 v194, v126, v128, v54
	v_fma_f32 v195, v126, v129, v6
	v_fma_f32 v194, -v127, v129, v194
	v_fma_f32 v195, v127, v128, v195
	v_bfe_u32 v196, v194, 16, 1
	v_bfe_u32 v197, v195, 16, 1
	v_add3_u32 v196, v194, v196, s6
	v_add3_u32 v197, v195, v197, s6
	ds_write_b16_d16_hi v145, v196 offset:2720
	ds_write_b16_d16_hi v145, v197 offset:2848
	v_fma_f32 v128, v126, v194, v55
	v_fma_f32 v129, v126, v195, v7
	v_fma_f32 v128, -v127, v195, v128
	v_fma_f32 v129, v127, v194, v129
	v_bfe_u32 v196, v128, 16, 1
	v_bfe_u32 v197, v129, 16, 1
	v_add3_u32 v196, v128, v196, s6
	v_add3_u32 v197, v129, v197, s6
	ds_write_b16_d16_hi v145, v196 offset:2992
	ds_write_b16_d16_hi v145, v197 offset:3120
	v_fma_f32 v194, v126, v128, v36
	v_fma_f32 v195, v126, v129, v20
	v_fma_f32 v194, -v127, v129, v194
	v_fma_f32 v195, v127, v128, v195
	v_bfe_u32 v196, v194, 16, 1
	v_bfe_u32 v197, v195, 16, 1
	v_add3_u32 v196, v194, v196, s6
	v_add3_u32 v197, v195, v197, s6
	ds_write_b16_d16_hi v145, v196 offset:3264
	ds_write_b16_d16_hi v145, v197 offset:3392
	v_fma_f32 v128, v126, v194, v37
	v_fma_f32 v129, v126, v195, v21
	v_fma_f32 v128, -v127, v195, v128
	v_fma_f32 v129, v127, v194, v129
	v_bfe_u32 v196, v128, 16, 1
	v_bfe_u32 v197, v129, 16, 1
	v_add3_u32 v196, v128, v196, s6
	v_add3_u32 v197, v129, v197, s6
	ds_write_b16_d16_hi v145, v196 offset:3536
	ds_write_b16_d16_hi v145, v197 offset:3664
	v_fma_f32 v194, v126, v128, v38
	v_fma_f32 v195, v126, v129, v22
	v_fma_f32 v194, -v127, v129, v194
	v_fma_f32 v195, v127, v128, v195
	v_bfe_u32 v196, v194, 16, 1
	v_bfe_u32 v197, v195, 16, 1
	v_add3_u32 v196, v194, v196, s6
	v_add3_u32 v197, v195, v197, s6
	ds_write_b16_d16_hi v145, v196 offset:3808
	ds_write_b16_d16_hi v145, v197 offset:3936
	v_fma_f32 v128, v126, v194, v39
	v_fma_f32 v129, v126, v195, v23
	v_fma_f32 v128, -v127, v195, v128
	v_fma_f32 v129, v127, v194, v129
	v_bfe_u32 v196, v128, 16, 1
	v_bfe_u32 v197, v129, 16, 1
	v_add3_u32 v196, v128, v196, s6
	v_add3_u32 v197, v129, v197, s6
	ds_write_b16_d16_hi v145, v196 offset:4080
	ds_write_b16_d16_hi v145, v197 offset:4208
	v_fma_f32 v194, v126, v128, v56
	v_fma_f32 v195, v126, v129, v8
	v_fma_f32 v194, -v127, v129, v194
	v_fma_f32 v195, v127, v128, v195
	v_bfe_u32 v196, v194, 16, 1
	v_bfe_u32 v197, v195, 16, 1
	v_add3_u32 v196, v194, v196, s6
	v_add3_u32 v197, v195, v197, s6
	ds_write_b16_d16_hi v145, v196 offset:4352
	ds_write_b16_d16_hi v145, v197 offset:4480
	v_fma_f32 v128, v126, v194, v57
	v_fma_f32 v129, v126, v195, v9
	v_fma_f32 v128, -v127, v195, v128
	v_fma_f32 v129, v127, v194, v129
	v_bfe_u32 v196, v128, 16, 1
	v_bfe_u32 v197, v129, 16, 1
	v_add3_u32 v196, v128, v196, s6
	v_add3_u32 v197, v129, v197, s6
	ds_write_b16_d16_hi v145, v196 offset:4624
	ds_write_b16_d16_hi v145, v197 offset:4752
	v_fma_f32 v194, v126, v128, v58
	v_fma_f32 v195, v126, v129, v10
	v_fma_f32 v194, -v127, v129, v194
	v_fma_f32 v195, v127, v128, v195
	v_bfe_u32 v196, v194, 16, 1
	v_bfe_u32 v197, v195, 16, 1
	v_add3_u32 v196, v194, v196, s6
	v_add3_u32 v197, v195, v197, s6
	ds_write_b16_d16_hi v145, v196 offset:4896
	ds_write_b16_d16_hi v145, v197 offset:5024
	v_fma_f32 v128, v126, v194, v59
	v_fma_f32 v129, v126, v195, v11
	v_fma_f32 v128, -v127, v195, v128
	v_fma_f32 v129, v127, v194, v129
	v_bfe_u32 v196, v128, 16, 1
	v_bfe_u32 v197, v129, 16, 1
	v_add3_u32 v196, v128, v196, s6
	v_add3_u32 v197, v129, v197, s6
	ds_write_b16_d16_hi v145, v196 offset:5168
	ds_write_b16_d16_hi v145, v197 offset:5296
	v_fma_f32 v194, v126, v128, v40
	v_fma_f32 v195, v126, v129, v24
	v_fma_f32 v194, -v127, v129, v194
	v_fma_f32 v195, v127, v128, v195
	v_bfe_u32 v196, v194, 16, 1
	v_bfe_u32 v197, v195, 16, 1
	v_add3_u32 v196, v194, v196, s6
	v_add3_u32 v197, v195, v197, s6
	ds_write_b16_d16_hi v145, v196 offset:5440
	ds_write_b16_d16_hi v145, v197 offset:5568
	v_fma_f32 v128, v126, v194, v41
	v_fma_f32 v129, v126, v195, v25
	v_fma_f32 v128, -v127, v195, v128
	v_fma_f32 v129, v127, v194, v129
	v_bfe_u32 v196, v128, 16, 1
	v_bfe_u32 v197, v129, 16, 1
	v_add3_u32 v196, v128, v196, s6
	v_add3_u32 v197, v129, v197, s6
	ds_write_b16_d16_hi v145, v196 offset:5712
	ds_write_b16_d16_hi v145, v197 offset:5840
	v_fma_f32 v194, v126, v128, v42
	v_fma_f32 v195, v126, v129, v26
	v_fma_f32 v194, -v127, v129, v194
	v_fma_f32 v195, v127, v128, v195
	v_bfe_u32 v196, v194, 16, 1
	v_bfe_u32 v197, v195, 16, 1
	v_add3_u32 v196, v194, v196, s6
	v_add3_u32 v197, v195, v197, s6
	ds_write_b16_d16_hi v145, v196 offset:5984
	ds_write_b16_d16_hi v145, v197 offset:6112
	v_fma_f32 v128, v126, v194, v43
	v_fma_f32 v129, v126, v195, v27
	v_fma_f32 v128, -v127, v195, v128
	v_fma_f32 v129, v127, v194, v129
	v_bfe_u32 v196, v128, 16, 1
	v_bfe_u32 v197, v129, 16, 1
	v_add3_u32 v196, v128, v196, s6
	v_add3_u32 v197, v129, v197, s6
	ds_write_b16_d16_hi v145, v196 offset:6256
	ds_write_b16_d16_hi v145, v197 offset:6384
	v_fma_f32 v194, v126, v128, v60
	v_fma_f32 v195, v126, v129, v12
	v_fma_f32 v194, -v127, v129, v194
	v_fma_f32 v195, v127, v128, v195
	v_bfe_u32 v196, v194, 16, 1
	v_bfe_u32 v197, v195, 16, 1
	v_add3_u32 v196, v194, v196, s6
	v_add3_u32 v197, v195, v197, s6
	ds_write_b16_d16_hi v145, v196 offset:6528
	ds_write_b16_d16_hi v145, v197 offset:6656
	v_fma_f32 v128, v126, v194, v61
	v_fma_f32 v129, v126, v195, v13
	v_fma_f32 v128, -v127, v195, v128
	v_fma_f32 v129, v127, v194, v129
	v_bfe_u32 v196, v128, 16, 1
	v_bfe_u32 v197, v129, 16, 1
	v_add3_u32 v196, v128, v196, s6
	v_add3_u32 v197, v129, v197, s6
	ds_write_b16_d16_hi v145, v196 offset:6800
	ds_write_b16_d16_hi v145, v197 offset:6928
	v_fma_f32 v194, v126, v128, v62
; DI bf16_t f2bf(float x) { unsigned u = __float_as_uint(x); u += 0x7fffu + ((u >> 16) & 1u); return (bf16_t)(u >> 16); }
; template <bool PASS2>
; DI void s5_item(const Params& p, int l, int item, int lane, const bf16_t* ubuf, bf16_t* ybpre, bf16_t* xs, float* bus) {
;     ...
; #pragma unroll 4
;       for (int t = 0; t < 16; t++) {
;         const float bur = bus[lane * 17 + t], bui = bus[(64 + lane) * 17 + t];
;         const float nxr = ar * xr - ai * xi + bur, nxi = ar * xi + ai * xr + bui;
;         xr = nxr; xi = nxi;
;         if (PASS2) {
;           xs[(half * 16 + t) * XSP + lane] = f2bf(xr);
;           xs[(half * 16 + t) * XSP + 64 + lane] = f2bf(xi);
;         }
;       }
;     }
;     if (PASS2) {
;       __builtin_amdgcn_fence(__ATOMIC_RELEASE, "wavefront");
;       __builtin_amdgcn_wave_barrier();
;       __builtin_amdgcn_fence(__ATOMIC_ACQUIRE, "wavefront");
;       f32x16 acc;
; #pragma unroll
;       for (int i = 0; i < 16; i++) acc[i] = 0.f;
; #pragma unroll
;       for (int ks = 0; ks < 8; ks++) {
;         const bf16x8 xf = *(const bf16x8*)(xs + r * XSP + ks * 16 + hh * 8);
;         acc = __builtin_amdgcn_mfma_f32_32x32x16_bf16(cf[ks], xf, acc, 0, 0, 0);
;       }
	v_fma_f32 v195, v126, v129, v14
	v_fma_f32 v194, -v127, v129, v194
	v_fma_f32 v195, v127, v128, v195
	v_bfe_u32 v196, v194, 16, 1
	v_bfe_u32 v197, v195, 16, 1
	v_add3_u32 v196, v194, v196, s6
	v_add3_u32 v197, v195, v197, s6
	ds_write_b16_d16_hi v145, v196 offset:7072
	ds_write_b16_d16_hi v145, v197 offset:7200
	v_fma_f32 v128, v126, v194, v63
	v_fma_f32 v129, v126, v195, v15
	v_fma_f32 v128, -v127, v195, v128
	v_fma_f32 v129, v127, v194, v129
	v_bfe_u32 v196, v128, 16, 1
	v_bfe_u32 v197, v129, 16, 1
	v_add3_u32 v196, v128, v196, s6
	v_add3_u32 v197, v129, v197, s6
	ds_write_b16_d16_hi v145, v196 offset:7344
	ds_write_b16_d16_hi v145, v197 offset:7472
	v_fma_f32 v194, v126, v128, v44
	v_fma_f32 v195, v126, v129, v28
	v_fma_f32 v194, -v127, v129, v194
	v_fma_f32 v195, v127, v128, v195
	v_bfe_u32 v196, v194, 16, 1
	v_bfe_u32 v197, v195, 16, 1
	v_add3_u32 v196, v194, v196, s6
	v_add3_u32 v197, v195, v197, s6
	ds_write_b16_d16_hi v145, v196 offset:7616
	ds_write_b16_d16_hi v145, v197 offset:7744
	v_fma_f32 v128, v126, v194, v45
	v_fma_f32 v129, v126, v195, v29
	v_fma_f32 v128, -v127, v195, v128
	v_fma_f32 v129, v127, v194, v129
	v_bfe_u32 v196, v128, 16, 1
	v_bfe_u32 v197, v129, 16, 1
	v_add3_u32 v196, v128, v196, s6
	v_add3_u32 v197, v129, v197, s6
	ds_write_b16_d16_hi v145, v196 offset:7888
	ds_write_b16_d16_hi v145, v197 offset:8016
	v_fma_f32 v194, v126, v128, v46
	v_fma_f32 v195, v126, v129, v30
	v_fma_f32 v194, -v127, v129, v194
	v_fma_f32 v195, v127, v128, v195
	v_bfe_u32 v196, v194, 16, 1
	v_bfe_u32 v197, v195, 16, 1
	v_add3_u32 v196, v194, v196, s6
	v_add3_u32 v197, v195, v197, s6
	ds_write_b16_d16_hi v145, v196 offset:8160
	ds_write_b16_d16_hi v145, v197 offset:8288
	v_fma_f32 v128, v126, v194, v47
	v_fma_f32 v129, v126, v195, v31
	v_fma_f32 v128, -v127, v195, v128
	v_fma_f32 v129, v127, v194, v129
	v_bfe_u32 v196, v128, 16, 1
	v_bfe_u32 v197, v129, 16, 1
	v_add3_u32 v196, v128, v196, s6
	v_add3_u32 v197, v129, v197, s6
	ds_write_b16_d16_hi v145, v196 offset:8432
	ds_write_b16_d16_hi v145, v197 offset:8560
	ds_read_b128 v[0:3], v143
	ds_read_b128 v[16:19], v143 offset:32
	v_mov_b32_e32 v125, v115
	s_waitcnt lgkmcnt(1)
	v_mfma_f32_32x32x16_bf16 v[0:15], v[80:83], v[0:3], 0
	s_add_i32 s2, s14, 32
	s_cmpk_gt_u32 s14, 0x5f
	s_mov_b32 s14, s2
	s_waitcnt lgkmcnt(0)
	v_mfma_f32_32x32x16_bf16 v[0:15], v[84:87], v[16:19], v[0:15]
	ds_read_b128 v[16:19], v143 offset:64
	s_waitcnt lgkmcnt(0)
	v_mfma_f32_32x32x16_bf16 v[0:15], v[88:91], v[16:19], v[0:15]
	ds_read_b128 v[16:19], v143 offset:96
	s_waitcnt lgkmcnt(0)
	v_mfma_f32_32x32x16_bf16 v[0:15], v[92:95], v[16:19], v[0:15]
	ds_read_b128 v[16:19], v143 offset:128
	s_waitcnt lgkmcnt(0)
	v_mfma_f32_32x32x16_bf16 v[0:15], v[96:99], v[16:19], v[0:15]
	ds_read_b128 v[16:19], v143 offset:160
	s_waitcnt lgkmcnt(0)
	v_mfma_f32_32x32x16_bf16 v[0:15], v[100:103], v[16:19], v[0:15]
	ds_read_b128 v[16:19], v143 offset:192
	s_waitcnt lgkmcnt(0)
	v_mfma_f32_32x32x16_bf16 v[0:15], v[104:107], v[16:19], v[0:15]
	ds_read_b128 v[16:19], v143 offset:224
	s_waitcnt lgkmcnt(0)
	v_mfma_f32_32x32x16_bf16 v[0:15], v[108:111], v[16:19], v[0:15]
	s_nop 11
	v_lshl_add_u64 v[10:11], v[138:139], 0, v[124:125]
	v_mov_b32_e32 v23, v2
	v_mov_b32_e32 v2, v1
	v_mov_b32_e32 v22, v0
	v_lshl_add_u64 v[8:9], v[140:141], 1, v[136:137]
	s_waitcnt vmcnt(2)
; DI bf16_t f2bf(float x) { unsigned u = __float_as_uint(x); u += 0x7fffu + ((u >> 16) & 1u); return (bf16_t)(u >> 16); }
; DI float bf2f(bf16_t b) { return __uint_as_float(((unsigned)b) << 16); }
; template <bool PASS2>
; DI void s5_item(const Params& p, int l, int item, int lane, const bf16_t* ubuf, bf16_t* ybpre, bf16_t* xs, float* bus) {
;     ...
;       const size_t tok = tok0 + tb + r;
; #pragma unroll
;       for (int q = 0; q < 2; q++) {
;         const int c0 = 8 * q + 4 * hh;
;         const uint2 uu = *(const uint2*)(ubuf + tok * 512 + g * 16 + c0);
;         const float4 dd = *(const float4*)(p.in[I_S5_D] + l * 512 + g * 16 + c0);
;         const float u0 = bf2f((bf16_t)(uu.x & 0xffff)), u1 = bf2f((bf16_t)(uu.x >> 16));
;         const float u2 = bf2f((bf16_t)(uu.y & 0xffff)), u3 = bf2f((bf16_t)(uu.y >> 16));
;         const float o0 = gelu_tanh(acc[4 * q + 0] + dd.x * u0), o1 = gelu_tanh(acc[4 * q + 1] + dd.y * u1);
;         const float o2 = gelu_tanh(acc[4 * q + 2] + dd.z * u2), o3 = gelu_tanh(acc[4 * q + 3] + dd.w * u3);
;         uint2 pk;
;         pk.x = (unsigned)f2bf(o0) | ((unsigned)f2bf(o1) << 16);
;         pk.y = (unsigned)f2bf(o2) | ((unsigned)f2bf(o3) << 16);
;         *(uint2*)(ybpre + tok * 512 + g * 16 + c0) = pk;
;       }
;     }
;   }
	v_mov_b32_e32 v16, v220
	v_mov_b32_e32 v17, v221
	v_lshlrev_b32_e32 v19, 16, v17
	v_lshlrev_b32_e32 v18, 16, v16
	v_and_b32_e32 v17, 0xffff0000, v17
	v_and_b32_e32 v16, 0xffff0000, v16
	v_mov_b32_e32 v12, v212
	v_mov_b32_e32 v13, v213
	v_mov_b32_e32 v14, v214
	v_mov_b32_e32 v15, v215
	v_mov_b32_e32 v21, v14
	v_mov_b32_e32 v14, v13
	v_pk_fma_f32 v[2:3], v[14:15], v[16:17], v[2:3]
	v_mov_b32_e32 v20, v12
	v_mul_f32_e32 v1, 0x3d372713, v2
	v_mul_f32_e32 v1, v2, v1
	v_fma_f32 v1, v2, v1, v2
	v_mul_f32_e32 v1, 0x3f4c422a, v1
	v_add_f32_e32 v1, v1, v1
	v_mul_f32_e32 v1, 0x3fb8aa3b, v1
	v_exp_f32_e32 v1, v1
	v_pk_fma_f32 v[18:19], v[20:21], v[18:19], v[22:23]
	v_mul_f32_e32 v13, 0x3d372713, v3
	v_mul_f32_e32 v0, 0x3d372713, v18
	v_add_f32_e32 v1, 1.0, v1
	v_rcp_f32_e32 v12, v1
	v_mul_f32_e32 v1, 0x3d372713, v19
	v_mul_f32_e32 v0, v18, v0
	v_mul_f32_e32 v1, v19, v1
	v_fma_f32 v0, v18, v0, v18
	v_fma_f32 v1, v19, v1, v19
	v_mul_f32_e32 v13, v3, v13
	v_mul_f32_e32 v0, 0x3f4c422a, v0
	v_mul_f32_e32 v1, 0x3f4c422a, v1
	v_fma_f32 v13, v3, v13, v3
	v_add_f32_e32 v0, v0, v0
	v_add_f32_e32 v1, v1, v1
	v_mul_f32_e32 v13, 0x3f4c422a, v13
	v_mul_f32_e32 v0, 0x3fb8aa3b, v0
	v_mul_f32_e32 v1, 0x3fb8aa3b, v1
	v_add_f32_e32 v13, v13, v13
	v_exp_f32_e32 v0, v0
	v_exp_f32_e32 v1, v1
	v_mul_f32_e32 v13, 0x3fb8aa3b, v13
	v_exp_f32_e32 v13, v13
	v_add_f32_e32 v0, 1.0, v0
	v_add_f32_e32 v1, 1.0, v1
	v_rcp_f32_e32 v0, v0
	v_rcp_f32_e32 v1, v1
	v_add_f32_e32 v13, 1.0, v13
	v_rcp_f32_e32 v13, v13
	v_pk_mul_f32 v[14:15], v[18:19], 0.5 op_sel_hi:[1,0]
	v_pk_fma_f32 v[0:1], v[0:1], 2.0, 1.0 op_sel_hi:[1,0,0] neg_lo:[1,0,0] neg_hi:[1,0,0]
	v_pk_mul_f32 v[2:3], v[2:3], 0.5 op_sel_hi:[1,0]
	v_pk_add_f32 v[0:1], v[0:1], 1.0 op_sel_hi:[1,0]
	v_pk_fma_f32 v[12:13], v[12:13], 2.0, 1.0 op_sel_hi:[1,0,0] neg_lo:[1,0,0] neg_hi:[1,0,0]
	v_pk_mul_f32 v[0:1], v[14:15], v[0:1]
	v_pk_add_f32 v[12:13], v[12:13], 1.0 op_sel_hi:[1,0]
	v_mov_b32_e32 v17, v6
	v_pk_mul_f32 v[2:3], v[2:3], v[12:13]
	v_and_b32_sdwa v12, v1, v180 dst_sel:DWORD dst_unused:UNUSED_PAD src0_sel:WORD_1 src1_sel:DWORD
	v_and_b32_sdwa v13, v0, v180 dst_sel:DWORD dst_unused:UNUSED_PAD src0_sel:WORD_1 src1_sel:DWORD
	v_add3_u32 v0, v0, v13, s6
	v_add3_u32 v1, v1, v12, s6
	v_and_b32_sdwa v12, v3, v180 dst_sel:DWORD dst_unused:UNUSED_PAD src0_sel:WORD_1 src1_sel:DWORD
	v_and_b32_sdwa v13, v2, v180 dst_sel:DWORD dst_unused:UNUSED_PAD src0_sel:WORD_1 src1_sel:DWORD
	v_add3_u32 v3, v3, v12, s6
	v_add3_u32 v2, v2, v13, s6
	v_and_b32_e32 v3, 0xffff0000, v3
	v_and_b32_e32 v2, 0xffff0000, v2
	v_or_b32_sdwa v1, v3, v1 dst_sel:DWORD dst_unused:UNUSED_PAD src0_sel:DWORD src1_sel:WORD_1
	v_or_b32_sdwa v0, v2, v0 dst_sel:DWORD dst_unused:UNUSED_PAD src0_sel:DWORD src1_sel:WORD_1
	global_store_dwordx2 v[8:9], v[0:1], off
	s_nop 0
	v_mov_b32_e32 v6, v5
	v_mov_b32_e32 v16, v4
	s_waitcnt vmcnt(2)
	v_mov_b32_e32 v0, v222
	v_mov_b32_e32 v1, v223
	v_lshlrev_b32_e32 v3, 16, v1
	v_lshlrev_b32_e32 v2, 16, v0
	v_and_b32_e32 v1, 0xffff0000, v1
	v_and_b32_e32 v0, 0xffff0000, v0
	v_mov_b32_e32 v10, v216
	v_mov_b32_e32 v11, v217
	v_mov_b32_e32 v12, v218
	v_mov_b32_e32 v13, v219
	v_mov_b32_e32 v15, v12
	v_mov_b32_e32 v12, v11
	v_pk_fma_f32 v[0:1], v[12:13], v[0:1], v[6:7]
	v_mov_b32_e32 v14, v10
	v_mul_f32_e32 v5, 0x3d372713, v0
	v_mul_f32_e32 v5, v0, v5
	v_fma_f32 v5, v0, v5, v0
	v_mul_f32_e32 v5, 0x3f4c422a, v5
	v_add_f32_e32 v5, v5, v5
	v_mul_f32_e32 v5, 0x3fb8aa3b, v5
	v_exp_f32_e32 v5, v5
	v_pk_fma_f32 v[2:3], v[14:15], v[2:3], v[16:17]
	v_add_f32_e32 v5, 1.0, v5
	v_mul_f32_e32 v4, 0x3d372713, v2
	v_rcp_f32_e32 v6, v5
	v_mul_f32_e32 v5, 0x3d372713, v3
	v_mul_f32_e32 v4, v2, v4
	v_mul_f32_e32 v5, v3, v5
	v_fma_f32 v4, v2, v4, v2
	v_fma_f32 v5, v3, v5, v3
	v_mul_f32_e32 v4, 0x3f4c422a, v4
	v_mul_f32_e32 v5, 0x3f4c422a, v5
	v_add_f32_e32 v4, v4, v4
	v_add_f32_e32 v5, v5, v5
	v_mul_f32_e32 v4, 0x3fb8aa3b, v4
	v_mul_f32_e32 v5, 0x3fb8aa3b, v5
	v_exp_f32_e32 v4, v4
	v_exp_f32_e32 v5, v5
	v_pk_mul_f32 v[2:3], v[2:3], 0.5 op_sel_hi:[1,0]
	v_add_f32_e32 v4, 1.0, v4
	v_add_f32_e32 v5, 1.0, v5
	v_rcp_f32_e32 v4, v4
	v_rcp_f32_e32 v5, v5
	s_nop 0
	v_pk_fma_f32 v[4:5], v[4:5], 2.0, 1.0 op_sel_hi:[1,0,0] neg_lo:[1,0,0] neg_hi:[1,0,0]
	s_nop 0
	v_pk_add_f32 v[4:5], v[4:5], 1.0 op_sel_hi:[1,0]
	s_nop 0
	v_pk_mul_f32 v[2:3], v[2:3], v[4:5]
	v_mul_f32_e32 v4, 0x3d372713, v1
	v_mul_f32_e32 v4, v1, v4
	v_fma_f32 v4, v1, v4, v1
	v_mul_f32_e32 v4, 0x3f4c422a, v4
	v_add_f32_e32 v4, v4, v4
	v_mul_f32_e32 v4, 0x3fb8aa3b, v4
	v_exp_f32_e32 v4, v4
	v_pk_mul_f32 v[0:1], v[0:1], 0.5 op_sel_hi:[1,0]
	v_add_f32_e32 v4, 1.0, v4
	v_rcp_f32_e32 v7, v4
	s_nop 0
	v_pk_fma_f32 v[4:5], v[6:7], 2.0, 1.0 op_sel_hi:[1,0,0] neg_lo:[1,0,0] neg_hi:[1,0,0]
	s_nop 0
	v_pk_add_f32 v[4:5], v[4:5], 1.0 op_sel_hi:[1,0]
	s_nop 0
	v_pk_mul_f32 v[0:1], v[0:1], v[4:5]
	v_and_b32_sdwa v4, v3, v180 dst_sel:DWORD dst_unused:UNUSED_PAD src0_sel:WORD_1 src1_sel:DWORD
	v_and_b32_sdwa v5, v2, v180 dst_sel:DWORD dst_unused:UNUSED_PAD src0_sel:WORD_1 src1_sel:DWORD
	v_add3_u32 v2, v2, v5, s6
	v_add3_u32 v3, v3, v4, s6
	v_and_b32_sdwa v4, v1, v180 dst_sel:DWORD dst_unused:UNUSED_PAD src0_sel:WORD_1 src1_sel:DWORD
	v_and_b32_sdwa v5, v0, v180 dst_sel:DWORD dst_unused:UNUSED_PAD src0_sel:WORD_1 src1_sel:DWORD
	v_add3_u32 v1, v1, v4, s6
	v_add3_u32 v0, v0, v5, s6
	v_and_b32_e32 v1, 0xffff0000, v1
	v_and_b32_e32 v0, 0xffff0000, v0
	v_or_b32_sdwa v1, v1, v3 dst_sel:DWORD dst_unused:UNUSED_PAD src0_sel:DWORD src1_sel:WORD_1
	v_or_b32_sdwa v0, v0, v2 dst_sel:DWORD dst_unused:UNUSED_PAD src0_sel:DWORD src1_sel:WORD_1
	global_store_dwordx2 v[8:9], v[0:1], off offset:16
	s_cbranch_scc0 .LBB0_2662
	v_readlane_b32 s0, v252, 27
	v_readlane_b32 s1, v252, 28
	s_nop 0
	v_add_u32_e32 v142, s0, v142
	s_movk_i32 s0, 0x1fff
	v_cmp_lt_i32_e64 s[0:1], s0, v142
	s_or_b64 s[12:13], s[0:1], s[12:13]
	s_andn2_b64 exec, exec, s[12:13]
	s_cbranch_execnz .LBB0_2535
	s_branch .LBB0_2674
